# plus: attention q_norm gain loads hoisted out of the head loop; sg unit z_u and statistics loads issued together instead of one per block
# speedup vs baseline: 1.0234x; 1.0046x over previous
; __device__ __forceinline__ void attn_unit(LAS unsigned char* lds, const bf16_t* PROJ, bf16_t* YCAT, const float* qg, const float* kg, const float* sinks, int unit, int tid, int wave, int lane) {
;     ...
;     const int fr = lane & 15, fq = lane >> 4, qrow = 16 * wave + fr;
;     u32x4 qnx[4];
;     {
;         const bf16_t* qp0 = PROJ + (size_t)(t0 + qrow) * INW + (4 * kvh) * 128 + 8 * fq;
; #pragma unroll
;         for (int ks = 0; ks < 4; ++ks) qnx[ks] = *(const u32x4*)(qp0 + 32 * ks);
;     }
;     ...
;     for (int rel = 0; rel < 10; ++rel)
; #pragma unroll
;         for (int i = 0; i < 4; ++i) {
;             const int kidx = 16 * (wp + rel) + 4 * fq + i, dist = qidx - kidx;
;             const bool valid = (dist >= 0) && (dist < 128) && (blk > 0 || kidx >= 128);
.LBB0_171:
	v_writelane_b32 v255, s24, 45
	v_add_u32_e32 v2, s14, v145
	v_ashrrev_i32_e32 v3, 31, v2
	v_writelane_b32 v255, s25, 46
	v_cndmask_b32_e64 v4, 0, 1, s[24:25]
	v_readlane_b32 s2, v255, 43
	v_lshlrev_b32_e32 v0, 4, v4
	v_readlane_b32 s3, v255, 44
	v_lshlrev_b64 v[2:3], 12, v[2:3]
	v_lshl_or_b32 v2, v4, 10, v2
	v_lshl_add_u64 v[88:89], s[2:3], 0, v[0:1]
	s_lshl_b32 s2, s83, 6
	s_and_b32 s2, s2, 0xffffe000
	s_or_b32 s2, s13, s2
	v_lshl_add_u64 v[90:91], v[84:85], 0, v[2:3]
	v_add_u32_e32 v0, s2, v73
	v_mov_b64_e32 v[2:3], s[68:69]
	v_mad_i64_i32 v[2:3], s[2:3], v0, s81, v[2:3]
	s_lshl_b32 s78, s12, 10
	v_lshl_add_u64 v[4:5], v[2:3], 0, s[78:79]
	v_mov_b32_e32 v87, v1
	v_lshl_add_u64 v[4:5], v[4:5], 0, v[86:87]
	s_waitcnt lgkmcnt(0)
	s_barrier
	global_load_dwordx4 v[30:33], v[4:5], off
	global_load_dwordx4 v[26:29], v[4:5], off offset:64
	global_load_dwordx4 v[18:21], v[4:5], off offset:128
	global_load_dwordx4 v[22:25], v[4:5], off offset:192
	v_writelane_b32 v254, s20, 6
	s_lshl_b32 s78, s12, 2
	s_add_i32 s86, s78, 4
	v_writelane_b32 v254, s21, 7
	s_cmp_lg_u32 s66, 0
	v_readlane_b32 s10, v254, 31
	v_readlane_b32 s18, v254, 41
	s_cselect_b64 s[2:3], -1, 0
	v_readlane_b32 s8, v252, 32
	v_readlane_b32 s11, v254, 32
	v_readlane_b32 s12, v254, 29
	v_readlane_b32 s19, v254, 42
	v_readlane_b32 s20, v254, 39
	v_readlane_b32 s9, v252, 33
	s_or_b64 s[10:11], s[10:11], s[2:3]
	v_readlane_b32 s13, v254, 30
	s_or_b64 s[18:19], s[18:19], s[2:3]
	v_readlane_b32 s21, v254, 40
	s_or_b64 s[22:23], s[8:9], s[2:3]
	v_readlane_b32 s8, v254, 27
	s_and_b64 s[10:11], s[12:13], s[10:11]
	v_readlane_b32 s12, v254, 33
	v_readlane_b32 s14, v254, 35
	v_readlane_b32 s16, v254, 37
	s_and_b64 s[18:19], s[20:21], s[18:19]
	v_readlane_b32 s20, v254, 43
	v_readlane_b32 s24, v254, 45
	v_readlane_b32 s9, v254, 28
	v_readlane_b32 s13, v254, 34
	v_readlane_b32 s15, v254, 36
	v_readlane_b32 s17, v254, 38
	v_readlane_b32 s21, v254, 44
	v_readlane_b32 s25, v254, 46
	v_readlane_b32 s26, v254, 51
	s_and_b64 s[8:9], s[8:9], s[22:23]
	s_and_b64 s[12:13], s[12:13], s[22:23]
	s_and_b64 s[14:15], s[14:15], s[22:23]
	s_and_b64 s[16:17], s[16:17], s[22:23]
	s_and_b64 s[20:21], s[20:21], s[22:23]
	s_and_b64 s[22:23], s[24:25], s[22:23]
	v_readlane_b32 s24, v252, 34
	v_readlane_b32 s27, v254, 52
	v_readlane_b32 s28, v254, 49
	v_readlane_b32 s25, v252, 35
	s_or_b64 s[26:27], s[26:27], s[2:3]
	v_readlane_b32 s29, v254, 50
	s_or_b64 s[30:31], s[24:25], s[2:3]
	v_readlane_b32 s24, v254, 47
	s_and_b64 s[26:27], s[28:29], s[26:27]
	v_readlane_b32 s28, v254, 53
	v_readlane_b32 s34, v254, 55
	v_readlane_b32 s25, v254, 48
	v_readlane_b32 s29, v254, 54
	v_readlane_b32 s35, v254, 56
	v_readlane_b32 s36, v254, 61
	s_and_b64 s[24:25], s[24:25], s[30:31]
	s_and_b64 s[28:29], s[28:29], s[30:31]
	s_and_b64 s[30:31], s[34:35], s[30:31]
	v_readlane_b32 s34, v252, 36
	v_readlane_b32 s37, v254, 62
	v_readlane_b32 s38, v254, 59
	v_readlane_b32 s35, v252, 37
	s_or_b64 s[36:37], s[36:37], s[2:3]
	v_readlane_b32 s39, v254, 60
	s_or_b64 s[40:41], s[34:35], s[2:3]
	v_readlane_b32 s34, v254, 57
	s_and_b64 s[36:37], s[38:39], s[36:37]
	v_readlane_b32 s38, v254, 63
	v_readlane_b32 s42, v255, 1
	v_readlane_b32 s35, v254, 58
	v_readlane_b32 s39, v255, 0
	v_readlane_b32 s43, v255, 2
	v_readlane_b32 s44, v255, 7
	s_and_b64 s[34:35], s[34:35], s[40:41]
	s_and_b64 s[38:39], s[38:39], s[40:41]
	s_and_b64 s[40:41], s[42:43], s[40:41]
	v_readlane_b32 s42, v252, 38
	v_readlane_b32 s45, v255, 8
	v_readlane_b32 s46, v255, 5
	v_readlane_b32 s43, v252, 39
	s_or_b64 s[44:45], s[44:45], s[2:3]
	v_readlane_b32 s47, v255, 6
	s_or_b64 s[48:49], s[42:43], s[2:3]
	v_readlane_b32 s42, v255, 3
	s_and_b64 s[44:45], s[46:47], s[44:45]
	v_readlane_b32 s46, v255, 9
	v_readlane_b32 s50, v255, 11
	v_readlane_b32 s43, v255, 4
	v_readlane_b32 s47, v255, 10
	v_readlane_b32 s51, v255, 12
	v_readlane_b32 s52, v255, 17
	s_and_b64 s[42:43], s[42:43], s[48:49]
	s_and_b64 s[46:47], s[46:47], s[48:49]
	s_and_b64 s[48:49], s[50:51], s[48:49]
	v_readlane_b32 s50, v252, 41
	v_readlane_b32 s53, v255, 18
	v_readlane_b32 s54, v255, 15
	v_readlane_b32 s51, v252, 42
	s_or_b64 s[52:53], s[52:53], s[2:3]
	v_readlane_b32 s55, v255, 16
	s_or_b64 s[56:57], s[50:51], s[2:3]
	v_readlane_b32 s50, v255, 13
	s_and_b64 s[52:53], s[54:55], s[52:53]
	v_readlane_b32 s54, v255, 19
	v_readlane_b32 s58, v255, 21
	v_readlane_b32 s51, v255, 14
	v_readlane_b32 s55, v255, 20
	v_readlane_b32 s59, v255, 22
	v_readlane_b32 s60, v255, 27
	s_and_b64 s[50:51], s[50:51], s[56:57]
	s_and_b64 s[54:55], s[54:55], s[56:57]
	s_and_b64 s[56:57], s[58:59], s[56:57]
	v_readlane_b32 s58, v252, 43
	v_readlane_b32 s61, v255, 28
	v_readlane_b32 s62, v255, 25
	v_readlane_b32 s59, v252, 44
	s_or_b64 s[60:61], s[60:61], s[2:3]
	v_readlane_b32 s63, v255, 26
	s_or_b64 s[64:65], s[58:59], s[2:3]
	v_readlane_b32 s58, v255, 23
	s_and_b64 s[60:61], s[62:63], s[60:61]
	v_readlane_b32 s62, v255, 29
	v_readlane_b32 s68, v255, 31
	v_readlane_b32 s59, v255, 24
	v_readlane_b32 s63, v255, 30
	v_readlane_b32 s69, v255, 32
	v_readlane_b32 s67, v252, 40
	s_and_b64 s[58:59], s[58:59], s[64:65]
	s_and_b64 s[62:63], s[62:63], s[64:65]
	s_and_b64 s[64:65], s[68:69], s[64:65]
	s_or_b32 s66, s66, s67
	v_readlane_b32 s68, v255, 37
	s_cmp_lg_u32 s66, 0
	v_readlane_b32 s69, v255, 38
	s_cselect_b64 s[72:73], -1, 0
	s_or_b64 s[2:3], s[68:69], s[2:3]
	v_readlane_b32 s68, v255, 35
	v_readlane_b32 s69, v255, 36
	s_and_b64 s[68:69], s[68:69], s[2:3]
	v_readlane_b32 s2, v255, 39
	v_readlane_b32 s3, v255, 40
	v_readlane_b32 s66, v255, 33
	s_and_b64 s[70:71], s[2:3], s[72:73]
	v_readlane_b32 s2, v255, 41
	v_readlane_b32 s67, v255, 34
	v_readlane_b32 s3, v255, 42
	v_lshl_add_u64 v[92:93], v[2:3], 0, v[86:87]
	s_mov_b32 s76, 0x800000
	s_and_b64 s[66:67], s[66:67], s[72:73]
	s_and_b64 s[72:73], s[2:3], s[72:73]
	s_mov_b64 s[2:3], 0
	global_load_dwordx4 v[208:211], v[80:81], off
	global_load_dwordx4 v[212:215], v[80:81], off offset:16
	global_load_dwordx4 v[216:219], v[80:81], off offset:128
	global_load_dwordx4 v[220:223], v[80:81], off offset:144
	global_load_dwordx4 v[224:227], v[80:81], off offset:256
	global_load_dwordx4 v[228:231], v[80:81], off offset:272
	global_load_dwordx4 v[232:235], v[80:81], off offset:384
	global_load_dwordx4 v[236:239], v[80:81], off offset:400
	s_waitcnt vmcnt(0)
; __device__ __forceinline__ u32x4 pack8(f32x4 a, f32x4 b) { u32x4 w; w.x = cvt_pk_bf16(a[0], a[1]); w.y = cvt_pk_bf16(a[2], a[3]); w.z = cvt_pk_bf16(b[0], b[1]); w.w = cvt_pk_bf16(b[2], b[3]); return w; }
; __device__ __forceinline__ void unpack8(u32x4 w, f32x4& a, f32x4& b) { a = (f32x4){bf_lo(w.x), bf_hi(w.x), bf_lo(w.y), bf_hi(w.y)}; b = (f32x4){bf_lo(w.z), bf_hi(w.z), bf_lo(w.w), bf_hi(w.w)}; }
; __device__ __forceinline__ void attn_unit(LAS unsigned char* lds, const bf16_t* PROJ, bf16_t* YCAT, const float* qg, const float* kg, const float* sinks, int unit, int tid, int wave, int lane) {
;     ...
;     for (int hq = 4 * kvh; hq < 4 * kvh + 4; ++hq) {
;     bf16x8 qf[4];
;     {
;         u32x4 w[4]; float ss = 0.f;
; #pragma unroll
;         for (int ks = 0; ks < 4; ++ks) w[ks] = qnx[ks];
;         {
;             const int hn = (hq + 1 < 4 * kvh + 4) ? hq + 1 : hq;
;             const bf16_t* qpn = PROJ + (size_t)(t0 + qrow) * INW + hn * 128 + 8 * fq;
; #pragma unroll
;             for (int ks = 0; ks < 4; ++ks) qnx[ks] = *(const u32x4*)(qpn + 32 * ks);
;         }
; #pragma unroll
;         for (int ks = 0; ks < 4; ++ks) { f32x4 v0, v1; pg8::unpack8(w[ks], v0, v1);
;             ss += (v0[0] * v0[0] + v0[1] * v0[1]) + (v0[2] * v0[2] + v0[3] * v0[3]) + (v1[0] * v1[0] + v1[1] * v1[1]) + (v1[2] * v1[2] + v1[3] * v1[3]); }
;         ss += __shfl_xor(ss, 16); ss += __shfl_xor(ss, 32);
;         const float rs = rsqrtf(ss * (1.f / 128.f) + EPS) * 0.08838834764831845f;
; #pragma unroll
;         for (int ks = 0; ks < 4; ++ks) { f32x4 v0, v1; pg8::unpack8(w[ks], v0, v1);
;             const f32x4 g0 = *(const f32x4*)(qg + 32 * ks + 8 * fq), g1 = *(const f32x4*)(qg + 32 * ks + 8 * fq + 4);
;             qf[ks] = as_bf8(pg8::pack8(v0 * rs * g0, v1 * rs * g1)); }
;     }
.LBB0_172:
	s_nop 0
	v_and_b32_e32 v51, 0xffff0000, v31
	v_and_b32_e32 v55, 0xffff0000, v30
	v_and_b32_e32 v54, 0xffff0000, v32
	v_lshlrev_b32_e32 v50, 16, v31
	v_mul_f32_e32 v0, v51, v51
	v_lshlrev_b32_e32 v53, 16, v30
	v_lshlrev_b32_e32 v52, 16, v32
	v_pk_mul_f32 v[30:31], v[54:55], v[54:55]
	v_pk_fma_f32 v[34:35], v[50:51], v[50:51], v[0:1] op_sel_hi:[1,1,0]
	v_pk_fma_f32 v[30:31], v[52:53], v[52:53], v[30:31]
	s_nop 0
	v_and_b32_e32 v39, 0xffff0000, v27
	v_pk_add_f32 v[34:35], v[30:31], v[34:35] op_sel:[1,0] op_sel_hi:[0,1]
	v_and_b32_e32 v38, 0xffff0000, v26
	v_pk_add_f32 v[42:43], v[30:31], v[34:35]
	v_lshlrev_b32_e32 v37, 16, v27
	v_lshlrev_b32_e32 v36, 16, v26
	v_pk_mul_f32 v[26:27], v[38:39], v[38:39]
	v_and_b32_e32 v35, 0xffff0000, v29
	v_and_b32_e32 v34, 0xffff0000, v28
	v_lshlrev_b32_e32 v56, 16, v33
	v_and_b32_e32 v57, 0xffff0000, v33
	v_pk_fma_f32 v[26:27], v[36:37], v[36:37], v[26:27]
	v_lshlrev_b32_e32 v33, 16, v29
	v_lshlrev_b32_e32 v32, 16, v28
	v_pk_mul_f32 v[28:29], v[34:35], v[34:35]
	s_nop 0
	v_and_b32_e32 v41, 0xffff0000, v18
	v_pk_add_f32 v[26:27], v[26:27], v[26:27] op_sel:[0,1] op_sel_hi:[1,0]
	v_pk_fma_f32 v[44:45], v[32:33], v[32:33], v[28:29]
	v_lshlrev_b32_e32 v40, 16, v18
	v_and_b32_e32 v59, 0xffff0000, v19
	v_mul_f32_e32 v0, v41, v41
	v_pk_add_f32 v[46:47], v[44:45], v[26:27]
	v_lshlrev_b32_e32 v58, 16, v19
	s_nop 0
	v_lshlrev_b32_e32 v26, 16, v23
	v_and_b32_e32 v27, 0xffff0000, v23
	v_pk_fma_f32 v[60:61], v[40:41], v[40:41], v[0:1] op_sel_hi:[1,1,0]
	v_mul_f32_e32 v0, v59, v59
	v_mul_f32_e32 v18, v26, v26
	v_mul_f32_e32 v64, v27, v27
	v_and_b32_e32 v31, 0xffff0000, v22
	v_and_b32_e32 v30, 0xffff0000, v20
	v_pk_mov_b32 v[48:49], v[20:21], v[24:25] op_sel:[1,0]
	v_pk_fma_f32 v[62:63], v[58:59], v[58:59], v[0:1] op_sel_hi:[1,1,0]
	v_lshlrev_b32_e32 v23, 16, v25
	v_and_b32_e32 v19, 0xffff0000, v25
	v_lshlrev_b32_e32 v29, 16, v22
	v_lshlrev_b32_e32 v28, 16, v20
	v_lshlrev_b32_e32 v25, 16, v24
	v_lshlrev_b32_e32 v24, 16, v21
	v_and_b32_e32 v21, 0xffff0000, v49
	v_and_b32_e32 v20, 0xffff0000, v48
	v_pk_mul_f32 v[48:49], v[30:31], v[30:31]
	v_mov_b32_e32 v61, v18
	v_mov_b32_e32 v63, v64
	v_pk_fma_f32 v[48:49], v[28:29], v[28:29], v[48:49]
	v_pk_add_f32 v[60:61], v[60:61], v[62:63]
	v_mul_f32_e32 v0, v57, v57
	v_pk_add_f32 v[48:49], v[48:49], v[60:61]
	v_pk_mul_f32 v[60:61], v[20:21], v[20:21]
	s_add_i32 s87, s78, 1
	v_pk_fma_f32 v[60:61], v[24:25], v[24:25], v[60:61]
	v_mov_b32_e32 v62, v42
	v_pk_add_f32 v[48:49], v[60:61], v[48:49]
	v_pk_fma_f32 v[60:61], v[56:57], v[56:57], v[0:1] op_sel_hi:[1,1,0]
	v_mov_b32_e32 v63, v23
	v_mov_b32_e32 v22, v60
	s_cmp_lt_u32 s87, s86
	v_mul_f32_e32 v65, v19, v19
	v_pk_add_f32 v[42:43], v[60:61], v[42:43]
	v_pk_mul_f32 v[60:61], v[22:23], v[62:63]
	v_pk_add_f32 v[44:45], v[44:45], v[46:47] op_sel:[1,0] op_sel_hi:[0,1]
	s_cselect_b32 s78, s87, s78
	v_mov_b32_e32 v43, v61
	v_mov_b32_e32 v45, v65
	s_lshl_b32 s78, s78, 7
	v_pk_add_f32 v[42:43], v[42:43], v[44:45]
	v_lshl_add_u64 v[14:15], s[78:79], 1, v[92:93]
	v_pk_add_f32 v[42:43], v[42:43], v[48:49]
	global_load_dwordx4 v[2:5], v[14:15], off
	global_load_dwordx4 v[6:9], v[14:15], off offset:64
	global_load_dwordx4 v[10:13], v[14:15], off offset:128
	s_nop 0
	global_load_dwordx4 v[14:17], v[14:15], off offset:192
	v_add_f32_e32 v0, v42, v43
	s_nop 0
	s_nop 0
	ds_bpermute_b32 v18, v100, v0
	v_mov_b32_e32 v60, v53
	v_mov_b32_e32 v61, v55
	v_mov_b32_e32 v53, v54
	v_mov_b32_e32 v54, v36
	s_waitcnt lgkmcnt(0)
	v_add_f32_e32 v0, v0, v18
	ds_bpermute_b32 v18, v101, v0
	v_mov_b32_e32 v55, v38
	v_mov_b32_e32 v38, v37
	s_mov_b32 s78, 0x42fc0000
	s_waitcnt lgkmcnt(0)
	v_add_f32_e32 v0, v0, v18
	v_fmamk_f32 v0, v0, 0x3c000000, v197
	v_cmp_gt_f32_e32 vcc, s76, v0
	v_mul_f32_e32 v18, 0x4b800000, v0
	s_nop 0
	v_cndmask_b32_e32 v0, v0, v18, vcc
	v_rsq_f32_e32 v0, v0
	s_nop 0
	v_mul_f32_e32 v18, 0x45800000, v0
	v_cndmask_b32_e32 v0, v0, v18, vcc
	v_mul_f32_e32 v0, 0x3db504f3, v0
	v_pk_mul_f32 v[50:51], v[0:1], v[50:51] op_sel_hi:[0,1]
	v_pk_mul_f32 v[60:61], v[0:1], v[60:61] op_sel_hi:[0,1]
	v_pk_mul_f32 v[54:55], v[0:1], v[54:55] op_sel_hi:[0,1]
	v_pk_mul_f32 v[36:37], v[0:1], v[38:39] op_sel_hi:[0,1]
	v_pk_mul_f32 v[40:41], v[0:1], v[40:41] op_sel_hi:[0,1]
	v_mov_b32_e32 v18, v23
	v_pk_mul_f32 v[18:19], v[0:1], v[18:19] op_sel_hi:[0,1]
	v_pk_mul_f32 v[26:27], v[0:1], v[26:27] op_sel_hi:[0,1]
	s_nop 0
	v_pk_mul_f32 v[48:49], v[210:211], v[50:51]
	v_pk_mul_f32 v[50:51], v[0:1], v[52:53] op_sel_hi:[0,1]
	v_pk_mul_f32 v[52:53], v[0:1], v[56:57] op_sel_hi:[0,1]
	v_pk_mul_f32 v[46:47], v[208:209], v[60:61]
	v_pk_mul_f32 v[52:53], v[214:215], v[52:53]
	v_pk_mul_f32 v[44:45], v[212:213], v[50:51]
	v_cvt_pk_bf16_f32 v42, v46, v47
	v_cvt_pk_bf16_f32 v43, v48, v49
	s_nop 0
	v_cvt_pk_bf16_f32 v44, v44, v45
	v_cvt_pk_bf16_f32 v45, v52, v53
	s_nop 0
	s_nop 0
	s_nop 0
	v_pk_mul_f32 v[38:39], v[216:217], v[54:55]
	v_mov_b32_e32 v50, v32
	v_mov_b32_e32 v51, v34
	v_mov_b32_e32 v34, v33
	v_pk_mul_f32 v[50:51], v[0:1], v[50:51] op_sel_hi:[0,1]
	v_pk_mul_f32 v[32:33], v[0:1], v[34:35] op_sel_hi:[0,1]
	v_pk_mul_f32 v[36:37], v[218:219], v[36:37]
	v_pk_mul_f32 v[32:33], v[222:223], v[32:33]
	v_pk_mul_f32 v[34:35], v[220:221], v[50:51]
	v_cvt_pk_bf16_f32 v62, v38, v39
	v_cvt_pk_bf16_f32 v63, v36, v37
	v_pk_mul_f32 v[46:47], v[0:1], v[58:59] op_sel_hi:[0,1]
	v_cvt_pk_bf16_f32 v64, v34, v35
	v_cvt_pk_bf16_f32 v65, v32, v33
	s_nop 0
	s_nop 0
	s_nop 0
	v_pk_mul_f32 v[38:39], v[226:227], v[46:47]
	v_pk_mul_f32 v[36:37], v[224:225], v[40:41]
	v_mov_b32_e32 v40, v28
	v_mov_b32_e32 v41, v30
	v_mov_b32_e32 v46, v24
	v_mov_b32_e32 v47, v20
	v_pk_mul_f32 v[40:41], v[0:1], v[40:41] op_sel_hi:[0,1]
	v_pk_mul_f32 v[46:47], v[0:1], v[46:47] op_sel_hi:[0,1]
	v_pk_mul_f32 v[34:35], v[230:231], v[46:47]
	v_pk_mul_f32 v[32:33], v[228:229], v[40:41]
	v_cvt_pk_bf16_f32 v58, v36, v37
	v_cvt_pk_bf16_f32 v59, v38, v39
	v_mov_b32_e32 v20, v25
	v_cvt_pk_bf16_f32 v60, v32, v33
	v_cvt_pk_bf16_f32 v61, v34, v35
	s_nop 0
	s_nop 0
	v_mov_b32_e32 v30, v29
	v_pk_mul_f32 v[20:21], v[0:1], v[20:21] op_sel_hi:[0,1]
	v_pk_mul_f32 v[28:29], v[0:1], v[30:31] op_sel_hi:[0,1]
	v_cvt_f32_u32_e32 v0, s87
	v_cmp_lt_f32_e32 vcc, s78, v0
	s_nop 0
	v_pk_mul_f32 v[18:19], v[18:19], v[238:239]
	v_pk_mul_f32 v[20:21], v[20:21], v[236:237]
	s_nop 0
	v_pk_mul_f32 v[26:27], v[26:27], v[234:235]
	v_pk_mul_f32 v[28:29], v[28:29], v[232:233]
	s_nop 0
	v_cvt_pk_bf16_f32 v66, v28, v29
	v_cvt_pk_bf16_f32 v67, v26, v27
	v_cvt_pk_bf16_f32 v68, v20, v21
	v_cvt_pk_bf16_f32 v69, v18, v19
	ds_read_b128 v[18:21], v146
	ds_read_b128 v[22:25], v146 offset:64
	s_waitcnt lgkmcnt(1)
; #define LAS __attribute__((address_space(3)))
; __device__ __forceinline__ void attn_unit(LAS unsigned char* lds, const bf16_t* PROJ, bf16_t* YCAT, const float* qg, const float* kg, const float* sinks, int unit, int tid, int wave, int lane) {
;     ...
;     const int wp = wave & ~1;
;     f32x4 s[10];
; #pragma unroll
;     for (int rel = 0; rel < 10; ++rel) {
;         s[rel] = (f32x4){0.f, 0.f, 0.f, 0.f};
; #pragma unroll
;         for (int ks = 0; ks < 4; ++ks) {
;             const bf16x8 kf = *(const LAS bf16x8*)(Ks + (16 * (wp + rel) + fr) * 136 + 32 * ks + 8 * fq);
;             s[rel] = __builtin_amdgcn_mfma_f32_16x16x32_bf16(kf, qf[ks], s[rel], 0, 0, 0);
;         }
;     }
	v_mfma_f32_16x16x32_bf16 v[18:21], v[18:21], v[42:45], 0
	ds_read_b128 v[170:173], v154 offset:64
	s_waitcnt lgkmcnt(1)
	v_mfma_f32_16x16x32_bf16 v[18:21], v[22:25], v[62:65], v[18:21]
	ds_read_b128 v[22:25], v146 offset:128
	s_waitcnt lgkmcnt(0)
	v_mfma_f32_16x16x32_bf16 v[18:21], v[22:25], v[58:61], v[18:21]
	ds_read_b128 v[22:25], v146 offset:192
	s_waitcnt lgkmcnt(0)
	v_mfma_f32_16x16x32_bf16 v[54:57], v[22:25], v[66:69], v[18:21]
	s_nop 4
	ds_read_b128 v[18:21], v147
	ds_read_b128 v[22:25], v147 offset:64
	s_waitcnt lgkmcnt(1)
	v_mfma_f32_16x16x32_bf16 v[18:21], v[18:21], v[42:45], 0
	s_waitcnt lgkmcnt(0)
	v_mfma_f32_16x16x32_bf16 v[18:21], v[22:25], v[62:65], v[18:21]
	ds_read_b128 v[22:25], v147 offset:128
	s_waitcnt lgkmcnt(0)
	v_mfma_f32_16x16x32_bf16 v[18:21], v[22:25], v[58:61], v[18:21]
	ds_read_b128 v[22:25], v147 offset:192
	s_waitcnt lgkmcnt(0)
	v_mfma_f32_16x16x32_bf16 v[50:53], v[22:25], v[66:69], v[18:21]
	s_nop 4
	ds_read_b128 v[18:21], v148
	ds_read_b128 v[22:25], v148 offset:64
	s_waitcnt lgkmcnt(1)
	v_mfma_f32_16x16x32_bf16 v[18:21], v[18:21], v[42:45], 0
	s_waitcnt lgkmcnt(0)
	v_mfma_f32_16x16x32_bf16 v[18:21], v[22:25], v[62:65], v[18:21]
	ds_read_b128 v[22:25], v148 offset:128
	s_waitcnt lgkmcnt(0)
	v_mfma_f32_16x16x32_bf16 v[18:21], v[22:25], v[58:61], v[18:21]
	ds_read_b128 v[22:25], v148 offset:192
	s_waitcnt lgkmcnt(0)
	v_mfma_f32_16x16x32_bf16 v[46:49], v[22:25], v[66:69], v[18:21]
	s_nop 4
	ds_read_b128 v[18:21], v149
	ds_read_b128 v[22:25], v149 offset:64
	s_waitcnt lgkmcnt(1)
	v_mfma_f32_16x16x32_bf16 v[18:21], v[18:21], v[42:45], 0
	s_waitcnt lgkmcnt(0)
	v_mfma_f32_16x16x32_bf16 v[18:21], v[22:25], v[62:65], v[18:21]
	ds_read_b128 v[22:25], v149 offset:128
	s_waitcnt lgkmcnt(0)
	v_mfma_f32_16x16x32_bf16 v[18:21], v[22:25], v[58:61], v[18:21]
	ds_read_b128 v[22:25], v149 offset:192
	s_waitcnt lgkmcnt(0)
	v_mfma_f32_16x16x32_bf16 v[38:41], v[22:25], v[66:69], v[18:21]
	s_nop 4
	ds_read_b128 v[18:21], v150
	ds_read_b128 v[22:25], v150 offset:64
	s_waitcnt lgkmcnt(1)
	v_mfma_f32_16x16x32_bf16 v[18:21], v[18:21], v[42:45], 0
	s_waitcnt lgkmcnt(0)
	v_mfma_f32_16x16x32_bf16 v[18:21], v[22:25], v[62:65], v[18:21]
	ds_read_b128 v[22:25], v150 offset:128
	s_waitcnt lgkmcnt(0)
	v_mfma_f32_16x16x32_bf16 v[18:21], v[22:25], v[58:61], v[18:21]
	ds_read_b128 v[22:25], v150 offset:192
	s_waitcnt lgkmcnt(0)
	v_mfma_f32_16x16x32_bf16 v[34:37], v[22:25], v[66:69], v[18:21]
	s_nop 4
	ds_read_b128 v[18:21], v151
	ds_read_b128 v[22:25], v151 offset:64
	s_waitcnt lgkmcnt(1)
	v_mfma_f32_16x16x32_bf16 v[18:21], v[18:21], v[42:45], 0
	s_waitcnt lgkmcnt(0)
	v_mfma_f32_16x16x32_bf16 v[18:21], v[22:25], v[62:65], v[18:21]
	ds_read_b128 v[22:25], v151 offset:128
	s_waitcnt lgkmcnt(0)
	v_mfma_f32_16x16x32_bf16 v[18:21], v[22:25], v[58:61], v[18:21]
	ds_read_b128 v[22:25], v151 offset:192
	s_waitcnt lgkmcnt(0)
	v_mfma_f32_16x16x32_bf16 v[30:33], v[22:25], v[66:69], v[18:21]
	s_nop 4
	ds_read_b128 v[18:21], v152
	ds_read_b128 v[22:25], v152 offset:64
	s_waitcnt lgkmcnt(1)
	v_mfma_f32_16x16x32_bf16 v[18:21], v[18:21], v[42:45], 0
	s_waitcnt lgkmcnt(0)
	v_mfma_f32_16x16x32_bf16 v[18:21], v[22:25], v[62:65], v[18:21]
	ds_read_b128 v[22:25], v152 offset:128
	s_waitcnt lgkmcnt(0)
	v_mfma_f32_16x16x32_bf16 v[18:21], v[22:25], v[58:61], v[18:21]
	ds_read_b128 v[22:25], v152 offset:192
	s_waitcnt lgkmcnt(0)
	v_mfma_f32_16x16x32_bf16 v[26:29], v[22:25], v[66:69], v[18:21]
	s_nop 4
	ds_read_b128 v[18:21], v153
	ds_read_b128 v[22:25], v153 offset:64
	s_waitcnt lgkmcnt(1)
	v_mfma_f32_16x16x32_bf16 v[18:21], v[18:21], v[42:45], 0
	s_waitcnt lgkmcnt(0)
	v_mfma_f32_16x16x32_bf16 v[18:21], v[22:25], v[62:65], v[18:21]
	ds_read_b128 v[22:25], v153 offset:128
	s_waitcnt lgkmcnt(0)
	v_mfma_f32_16x16x32_bf16 v[18:21], v[22:25], v[58:61], v[18:21]
	ds_read_b128 v[22:25], v153 offset:192
	s_waitcnt lgkmcnt(0)
	v_mfma_f32_16x16x32_bf16 v[22:25], v[22:25], v[66:69], v[18:21]
	s_nop 4
	ds_read_b128 v[18:21], v154
	s_waitcnt lgkmcnt(0)
	v_mfma_f32_16x16x32_bf16 v[18:21], v[18:21], v[42:45], 0
	v_mfma_f32_16x16x32_bf16 v[18:21], v[170:173], v[62:65], v[18:21]
	ds_read_b128 v[170:173], v154 offset:128
	s_waitcnt lgkmcnt(0)
	v_mfma_f32_16x16x32_bf16 v[18:21], v[170:173], v[58:61], v[18:21]
	ds_read_b128 v[170:173], v154 offset:192
	s_waitcnt lgkmcnt(0)
	v_mfma_f32_16x16x32_bf16 v[18:21], v[170:173], v[66:69], v[18:21]
	ds_read_b128 v[170:173], v155
	s_waitcnt lgkmcnt(0)
	v_mfma_f32_16x16x32_bf16 v[42:45], v[170:173], v[42:45], 0
	ds_read_b128 v[170:173], v155 offset:64
	s_waitcnt lgkmcnt(0)
	v_mfma_f32_16x16x32_bf16 v[42:45], v[170:173], v[62:65], v[42:45]
	ds_read_b128 v[62:65], v155 offset:128
	s_waitcnt lgkmcnt(0)
	v_mfma_f32_16x16x32_bf16 v[42:45], v[62:65], v[58:61], v[42:45]
	ds_read_b128 v[58:61], v155 offset:192
	s_waitcnt lgkmcnt(0)
; __device__ __forceinline__ void attn_unit(LAS unsigned char* lds, const bf16_t* PROJ, bf16_t* YCAT, const float* qg, const float* kg, const float* sinks, int unit, int tid, int wave, int lane) {
;     ...
;     const float slope = exp2f(-(float)(hq + 1)), sink = sinks[hq];
;     const int qidx = 128 + qrow;
;     float mx = -INFINITY;
; #pragma unroll
;     for (int rel = 0; rel < 10; ++rel)
; #pragma unroll
;         for (int i = 0; i < 4; ++i) {
;             const int kidx = 16 * (wp + rel) + 4 * fq + i, dist = qidx - kidx;
;             const bool valid = (dist >= 0) && (dist < 128) && (blk > 0 || kidx >= 128);
;             const float val = valid ? s[rel][i] - slope * (float)dist : -INFINITY;
;             s[rel][i] = val; mx = fmaxf(mx, val);
;         }
;     mx = fmaxf(mx, __shfl_xor(mx, 16)); mx = fmaxf(mx, __shfl_xor(mx, 32));
;     const float mm = fmaxf(mx, sink);
	v_mfma_f32_16x16x32_bf16 v[42:45], v[58:61], v[66:69], v[42:45]
	v_cndmask_b32_e32 v58, 0, v203, vcc
	v_sub_f32_e32 v0, v58, v0
	v_exp_f32_e32 v0, v0
	s_and_b64 vcc, vcc, exec
	s_cselect_b32 s78, 0xffffffc0, 0
	v_lshl_add_u64 v[60:61], v[88:89], 0, s[2:3]
	v_ldexp_f32 v58, v0, s78
	global_load_dword v0, v[60:61], off
	v_fma_f32 v54, -v58, v77, v54
	v_cndmask_b32_e64 v59, v204, v54, s[8:9]
	v_fma_f32 v54, -v58, v102, v55
	v_fma_f32 v56, -v58, v103, v56
	v_cndmask_b32_e64 v54, v204, v54, s[10:11]
	s_mov_b32 s78, 0xff800000
	v_cndmask_b32_e64 v174, v204, v56, s[12:13]
	v_fma_f32 v56, -v58, v104, v57
	v_fma_f32 v50, -v58, v105, v50
	v_max3_f32 v55, v59, s78, v54
	v_cndmask_b32_e64 v173, v204, v56, s[14:15]
	v_cndmask_b32_e64 v172, v204, v50, s[16:17]
	v_fma_f32 v50, -v58, v106, v51
	v_fma_f32 v51, -v58, v107, v52
	v_max3_f32 v55, v55, v174, v173
	v_cndmask_b32_e64 v171, v204, v50, s[18:19]
	v_cndmask_b32_e64 v170, v204, v51, s[20:21]
	v_fma_f32 v51, -v58, v108, v53
	v_fma_f32 v46, -v58, v109, v46
	v_max3_f32 v50, v55, v172, v171
	v_cndmask_b32_e64 v169, v204, v51, s[22:23]
	v_cndmask_b32_e64 v87, v204, v46, s[24:25]
	v_fma_f32 v46, -v58, v110, v47
	v_fma_f32 v47, -v58, v111, v48
	v_max3_f32 v50, v50, v170, v169
	v_cndmask_b32_e64 v69, v204, v46, s[26:27]
	v_cndmask_b32_e64 v68, v204, v47, s[28:29]
	v_fma_f32 v47, -v58, v112, v49
	v_fma_f32 v38, -v58, v113, v38
	v_max3_f32 v46, v50, v87, v69
	v_cndmask_b32_e64 v67, v204, v47, s[30:31]
	v_cndmask_b32_e64 v66, v204, v38, s[34:35]
	v_fma_f32 v38, -v58, v114, v39
	v_max3_f32 v46, v46, v68, v67
	v_cndmask_b32_e64 v64, v204, v38, s[36:37]
	v_fma_f32 v38, -v58, v115, v40
	v_fma_f32 v40, -v58, v116, v41
	v_fma_f32 v34, -v58, v117, v34
	v_max3_f32 v39, v46, v66, v64
	v_cndmask_b32_e64 v38, v204, v38, s[38:39]
	v_cndmask_b32_e64 v41, v204, v40, s[40:41]
	v_cndmask_b32_e64 v63, v204, v34, s[42:43]
	v_fma_f32 v34, -v58, v118, v35
	v_fma_f32 v35, -v58, v119, v36
	v_max3_f32 v39, v39, v38, v41
	v_cndmask_b32_e64 v62, v204, v34, s[44:45]
	v_cndmask_b32_e64 v61, v204, v35, s[46:47]
	v_fma_f32 v35, -v58, v120, v37
	v_fma_f32 v30, -v58, v121, v30
	v_max3_f32 v34, v39, v63, v62
	v_cndmask_b32_e64 v60, v204, v35, s[48:49]
	v_cndmask_b32_e64 v57, v204, v30, s[50:51]
	v_fma_f32 v30, -v58, v122, v31
	v_fma_f32 v31, -v58, v123, v32
	v_max3_f32 v34, v34, v61, v60
	v_cndmask_b32_e64 v56, v204, v30, s[52:53]
	v_cndmask_b32_e64 v55, v204, v31, s[54:55]
	v_fma_f32 v31, -v58, v124, v33
	v_fma_f32 v26, -v58, v125, v26
	v_max3_f32 v30, v34, v57, v56
	v_cndmask_b32_e64 v53, v204, v31, s[56:57]
	v_cndmask_b32_e64 v52, v204, v26, s[58:59]
	v_fma_f32 v26, -v58, v126, v27
	v_fma_f32 v27, -v58, v127, v28
	v_max3_f32 v30, v30, v55, v53
	v_cndmask_b32_e64 v51, v204, v26, s[60:61]
	v_cndmask_b32_e64 v50, v204, v27, s[62:63]
	v_fma_f32 v27, -v58, v128, v29
	v_fma_f32 v22, -v58, v129, v22
	v_fma_f32 v18, -v58, v133, v18
	v_max3_f32 v26, v30, v52, v51
	v_cndmask_b32_e64 v49, v204, v27, s[64:65]
	v_cndmask_b32_e64 v48, v204, v22, s[66:67]
	v_fma_f32 v22, -v58, v130, v23
	v_fma_f32 v23, -v58, v131, v24
	v_cndmask_b32_e64 v39, v204, v18, s[90:91]
	v_fma_f32 v18, -v58, v134, v19
	v_fma_f32 v19, -v58, v135, v20
	v_max3_f32 v26, v26, v50, v49
	v_cndmask_b32_e64 v47, v204, v22, s[68:69]
	v_cndmask_b32_e64 v46, v204, v23, s[70:71]
	v_fma_f32 v23, -v58, v132, v25
	v_cndmask_b32_e64 v36, v204, v19, s[94:95]
	v_fma_f32 v19, -v58, v136, v21
	v_max3_f32 v22, v26, v48, v47
	v_cndmask_b32_e64 v40, v204, v23, s[72:73]
	v_cndmask_b32_e64 v34, v204, v19, s[96:97]
	v_fma_f32 v19, -v58, v137, v42
	v_max3_f32 v22, v22, v46, v40
	v_cndmask_b32_e64 v37, v204, v18, s[92:93]
	v_cndmask_b32_e64 v33, v204, v19, s[4:5]
	v_fma_f32 v19, -v58, v138, v43
	v_max3_f32 v18, v22, v39, v37
	v_cndmask_b32_e64 v31, v204, v19, s[74:75]
	v_fma_f32 v19, -v58, v139, v44
	v_max3_f32 v18, v18, v36, v34
	v_cndmask_b32_e64 v30, v204, v19, s[6:7]
	v_fma_f32 v19, -v58, v140, v45
	v_max3_f32 v18, v18, v33, v31
	v_cndmask_b32_e64 v58, v204, v19, s[0:1]
	v_max3_f32 v18, v18, v30, v58
	ds_bpermute_b32 v19, v100, v18
	s_add_u32 s2, s2, 4
	s_addc_u32 s3, s3, 0
	s_cmp_lg_u32 s2, 16
	s_mov_b32 s78, s87
	s_waitcnt lgkmcnt(0)
	v_max_f32_e32 v19, v19, v19
	v_max_f32_e32 v18, v18, v19
	ds_bpermute_b32 v19, v101, v18
	s_waitcnt vmcnt(0) lgkmcnt(0)
; __device__ __forceinline__ u32x4 pack8(f32x4 a, f32x4 b) { u32x4 w; w.x = cvt_pk_bf16(a[0], a[1]); w.y = cvt_pk_bf16(a[2], a[3]); w.z = cvt_pk_bf16(b[0], b[1]); w.w = cvt_pk_bf16(b[2], b[3]); return w; }
; __device__ __forceinline__ void attn_unit(LAS unsigned char* lds, const bf16_t* PROJ, bf16_t* YCAT, const float* qg, const float* kg, const float* sinks, int unit, int tid, int wave, int lane) {
;     ...
;     const float mm = fmaxf(mx, sink);
;     float ls = 0.f;
; #pragma unroll
;     for (int rel = 0; rel < 10; ++rel)
; #pragma unroll
;         for (int i = 0; i < 4; ++i) { const float p = __expf(s[rel][i] - mm); s[rel][i] = p; ls += p; }
;     ls += __shfl_xor(ls, 16); ls += __shfl_xor(ls, 32);
;     const float inv = 1.f / (ls + __expf(sink - mm));
;     bf16x8 pf[5];
; #pragma unroll
;     for (int g = 0; g < 5; ++g) pf[g] = as_bf8(pg8::pack8(s[2 * g], s[2 * g + 1]));
	v_max3_f32 v65, v18, v19, v0
	v_sub_f32_e32 v18, v59, v65
	v_mul_f32_e32 v18, 0x3fb8aa3b, v18
	v_sub_f32_e32 v19, v54, v65
	v_exp_f32_e32 v18, v18
	v_mul_f32_e32 v19, 0x3fb8aa3b, v19
	v_exp_f32_e32 v19, v19
	v_sub_f32_e32 v38, v38, v65
	v_add_f32_e32 v20, 0, v18
	v_mul_f32_e32 v38, 0x3fb8aa3b, v38
	v_add_f32_e32 v21, v19, v20
	v_sub_f32_e32 v20, v174, v65
	v_mul_f32_e32 v20, 0x3fb8aa3b, v20
	v_exp_f32_e32 v20, v20
	v_sub_f32_e32 v41, v41, v65
	v_exp_f32_e32 v38, v38
	v_mul_f32_e32 v41, 0x3fb8aa3b, v41
	v_add_f32_e32 v22, v20, v21
	v_sub_f32_e32 v21, v173, v65
	v_mul_f32_e32 v21, 0x3fb8aa3b, v21
	v_exp_f32_e32 v21, v21
	v_exp_f32_e32 v41, v41
	v_sub_f32_e32 v56, v56, v65
	v_mul_f32_e32 v56, 0x3fb8aa3b, v56
	v_add_f32_e32 v23, v21, v22
	v_sub_f32_e32 v22, v172, v65
	v_mul_f32_e32 v22, 0x3fb8aa3b, v22
	v_exp_f32_e32 v22, v22
	v_sub_f32_e32 v55, v55, v65
	v_exp_f32_e32 v56, v56
	v_mul_f32_e32 v55, 0x3fb8aa3b, v55
	v_add_f32_e32 v24, v22, v23
	v_sub_f32_e32 v23, v171, v65
	v_mul_f32_e32 v23, 0x3fb8aa3b, v23
	v_exp_f32_e32 v23, v23
	v_sub_f32_e32 v53, v53, v65
	v_exp_f32_e32 v55, v55
	v_mul_f32_e32 v53, 0x3fb8aa3b, v53
	v_add_f32_e32 v25, v23, v24
	v_sub_f32_e32 v24, v170, v65
	v_mul_f32_e32 v24, 0x3fb8aa3b, v24
	v_exp_f32_e32 v24, v24
	v_sub_f32_e32 v52, v52, v65
	v_exp_f32_e32 v53, v53
	v_mul_f32_e32 v52, 0x3fb8aa3b, v52
	v_add_f32_e32 v26, v24, v25
	v_sub_f32_e32 v25, v169, v65
	v_mul_f32_e32 v25, 0x3fb8aa3b, v25
	v_exp_f32_e32 v25, v25
	v_sub_f32_e32 v51, v51, v65
	v_exp_f32_e32 v52, v52
	v_mul_f32_e32 v51, 0x3fb8aa3b, v51
	v_add_f32_e32 v27, v25, v26
	v_sub_f32_e32 v26, v87, v65
	v_mul_f32_e32 v26, 0x3fb8aa3b, v26
	v_exp_f32_e32 v26, v26
	v_sub_f32_e32 v50, v50, v65
	v_exp_f32_e32 v51, v51
	v_mul_f32_e32 v50, 0x3fb8aa3b, v50
	v_add_f32_e32 v28, v26, v27
	v_sub_f32_e32 v27, v69, v65
	v_mul_f32_e32 v27, 0x3fb8aa3b, v27
	v_exp_f32_e32 v27, v27
	v_sub_f32_e32 v49, v49, v65
	v_exp_f32_e32 v50, v50
	v_mul_f32_e32 v49, 0x3fb8aa3b, v49
	v_add_f32_e32 v29, v27, v28
	v_sub_f32_e32 v28, v68, v65
	v_mul_f32_e32 v28, 0x3fb8aa3b, v28
	v_exp_f32_e32 v28, v28
	v_sub_f32_e32 v48, v48, v65
	v_exp_f32_e32 v49, v49
	v_mul_f32_e32 v48, 0x3fb8aa3b, v48
	v_add_f32_e32 v32, v28, v29
	v_sub_f32_e32 v29, v67, v65
	v_mul_f32_e32 v29, 0x3fb8aa3b, v29
	v_exp_f32_e32 v29, v29
	v_sub_f32_e32 v47, v47, v65
	v_exp_f32_e32 v48, v48
	v_mul_f32_e32 v47, 0x3fb8aa3b, v47
	v_add_f32_e32 v35, v29, v32
	v_sub_f32_e32 v32, v66, v65
	v_mul_f32_e32 v32, 0x3fb8aa3b, v32
	v_exp_f32_e32 v32, v32
	v_sub_f32_e32 v46, v46, v65
	v_exp_f32_e32 v47, v47
	v_mul_f32_e32 v46, 0x3fb8aa3b, v46
	v_add_f32_e32 v42, v32, v35
	v_sub_f32_e32 v35, v64, v65
	v_mul_f32_e32 v35, 0x3fb8aa3b, v35
	v_exp_f32_e32 v35, v35
	v_sub_f32_e32 v40, v40, v65
	v_exp_f32_e32 v46, v46
	v_mul_f32_e32 v40, 0x3fb8aa3b, v40
	v_add_f32_e32 v42, v35, v42
	v_add_f32_e32 v42, v38, v42
	v_add_f32_e32 v43, v41, v42
	v_sub_f32_e32 v42, v63, v65
	v_mul_f32_e32 v42, 0x3fb8aa3b, v42
	v_exp_f32_e32 v42, v42
	v_sub_f32_e32 v39, v39, v65
	v_exp_f32_e32 v40, v40
	v_mul_f32_e32 v39, 0x3fb8aa3b, v39
	v_add_f32_e32 v44, v42, v43
	v_sub_f32_e32 v43, v62, v65
	v_mul_f32_e32 v43, 0x3fb8aa3b, v43
	v_exp_f32_e32 v43, v43
	v_sub_f32_e32 v37, v37, v65
	v_exp_f32_e32 v39, v39
	v_mul_f32_e32 v37, 0x3fb8aa3b, v37
	v_add_f32_e32 v45, v43, v44
	v_sub_f32_e32 v44, v61, v65
	v_mul_f32_e32 v44, 0x3fb8aa3b, v44
	v_exp_f32_e32 v44, v44
	v_sub_f32_e32 v36, v36, v65
	v_exp_f32_e32 v37, v37
	v_mul_f32_e32 v36, 0x3fb8aa3b, v36
	v_add_f32_e32 v54, v44, v45
	v_sub_f32_e32 v45, v60, v65
	v_mul_f32_e32 v45, 0x3fb8aa3b, v45
	v_exp_f32_e32 v45, v45
	v_sub_f32_e32 v34, v34, v65
	v_exp_f32_e32 v36, v36
	v_mul_f32_e32 v34, 0x3fb8aa3b, v34
	v_add_f32_e32 v59, v45, v54
	v_sub_f32_e32 v54, v57, v65
	v_mul_f32_e32 v54, 0x3fb8aa3b, v54
	v_exp_f32_e32 v54, v54
	v_sub_f32_e32 v33, v33, v65
	v_mul_f32_e32 v33, 0x3fb8aa3b, v33
	v_sub_f32_e32 v31, v31, v65
	v_add_f32_e32 v57, v54, v59
	v_add_f32_e32 v57, v56, v57
	v_add_f32_e32 v57, v55, v57
	v_add_f32_e32 v57, v53, v57
	v_add_f32_e32 v57, v52, v57
	v_add_f32_e32 v57, v51, v57
	v_add_f32_e32 v57, v50, v57
	v_add_f32_e32 v57, v49, v57
	v_add_f32_e32 v57, v48, v57
	v_add_f32_e32 v57, v47, v57
	v_add_f32_e32 v57, v46, v57
	v_add_f32_e32 v57, v40, v57
	v_exp_f32_e32 v59, v34
	v_add_f32_e32 v57, v39, v57
	v_add_f32_e32 v57, v37, v57
	v_add_f32_e32 v57, v36, v57
	v_add_f32_e32 v34, v59, v57
	v_exp_f32_e32 v57, v33
	v_mul_f32_e32 v31, 0x3fb8aa3b, v31
	v_sub_f32_e32 v30, v30, v65
	v_exp_f32_e32 v60, v31
	v_mul_f32_e32 v30, 0x3fb8aa3b, v30
	v_exp_f32_e32 v61, v30
	v_add_f32_e32 v33, v57, v34
	v_add_f32_e32 v31, v60, v33
	v_sub_f32_e32 v0, v0, v65
	v_add_f32_e32 v30, v61, v31
	v_sub_f32_e32 v31, v58, v65
	v_mul_f32_e32 v31, 0x3fb8aa3b, v31
	v_exp_f32_e32 v58, v31
	v_mul_f32_e32 v0, 0x3fb8aa3b, v0
	v_exp_f32_e32 v0, v0
	v_cvt_pk_bf16_f32 v18, v18, v19
	v_add_f32_e32 v30, v58, v30
	ds_bpermute_b32 v31, v100, v30
	v_cvt_pk_bf16_f32 v19, v20, v21
	v_cvt_pk_bf16_f32 v20, v22, v23
	v_cvt_pk_bf16_f32 v21, v24, v25
	v_cvt_pk_bf16_f32 v22, v26, v27
	s_waitcnt lgkmcnt(0)
	v_add_f32_e32 v30, v30, v31
	ds_bpermute_b32 v31, v101, v30
	v_cvt_pk_bf16_f32 v23, v28, v29
	v_cvt_pk_bf16_f32 v24, v32, v35
	v_cvt_pk_bf16_f32 v25, v38, v41
	v_cvt_pk_bf16_f32 v26, v42, v43
	s_waitcnt lgkmcnt(0)
; __device__ __forceinline__ unsigned cvt_pk_bf16(float lo, float hi) { unsigned r; asm volatile("v_cvt_pk_bf16_f32 %0, %1, %2" : "=v"(r) : "v"(lo), "v"(hi)); return r; }
; __device__ __forceinline__ u32x4 pack8(f32x4 a, f32x4 b) { u32x4 w; w.x = cvt_pk_bf16(a[0], a[1]); w.y = cvt_pk_bf16(a[2], a[3]); w.z = cvt_pk_bf16(b[0], b[1]); w.w = cvt_pk_bf16(b[2], b[3]); return w; }
; #define LAS __attribute__((address_space(3)))
; __device__ __forceinline__ void attn_unit(LAS unsigned char* lds, const bf16_t* PROJ, bf16_t* YCAT, const float* qg, const float* kg, const float* sinks, int unit, int tid, int wave, int lane) {
;     ...
;     ls += __shfl_xor(ls, 16); ls += __shfl_xor(ls, 32);
;     const float inv = 1.f / (ls + __expf(sink - mm));
;     bf16x8 pf[5];
; #pragma unroll
;     for (int g = 0; g < 5; ++g) pf[g] = as_bf8(pg8::pack8(s[2 * g], s[2 * g + 1]));
;     bf16_t* op = YCAT + (size_t)(t0 + qrow) * D + hq * 128 + 4 * fq;
; #pragma unroll
;     for (int db = 0; db < 8; ++db) {
;         f32x4 o = (f32x4){0.f, 0.f, 0.f, 0.f};
; #pragma unroll
;         for (int g = 0; g < 5; ++g) {
;             const bf16x8 vf = *(const LAS bf16x8*)(Vt + (16 * db + fr) * 264 + 32 * ((wp >> 1) + g) + 8 * fq);
;             o = __builtin_amdgcn_mfma_f32_16x16x32_bf16(vf, pf[g], o, 0, 0, 0);
;         }
;         u32x2 w; w.x = cvt_pk_bf16(o[0] * inv, o[1] * inv); w.y = cvt_pk_bf16(o[2] * inv, o[3] * inv);
;         *(u32x2*)(op + 16 * db) = w;
;     }
	v_add_f32_e32 v30, v30, v31
	v_add_f32_e32 v0, v0, v30
	v_div_scale_f32 v38, vcc, v0, v0, 1.0
	v_cvt_pk_bf16_f32 v27, v44, v45
	v_cvt_pk_bf16_f32 v28, v54, v56
	v_cvt_pk_bf16_f32 v29, v55, v53
	v_cvt_pk_bf16_f32 v30, v52, v51
	v_cvt_pk_bf16_f32 v31, v50, v49
	v_cvt_pk_bf16_f32 v32, v48, v47
	v_cvt_pk_bf16_f32 v33, v46, v40
	v_cvt_pk_bf16_f32 v34, v39, v37
	v_rcp_f32_e32 v39, v38
	v_cvt_pk_bf16_f32 v35, v36, v59
	v_cvt_pk_bf16_f32 v36, v57, v60
	v_cvt_pk_bf16_f32 v37, v61, v58
	s_nop 0
	v_fma_f32 v40, -v38, v39, 1.0
	v_fmac_f32_e32 v39, v40, v39
	v_div_scale_f32 v40, vcc, 1.0, v0, 1.0
	v_mul_f32_e32 v41, v40, v39
	v_fma_f32 v42, -v38, v41, v40
	v_fmac_f32_e32 v41, v42, v39
	v_fma_f32 v38, -v38, v41, v40
	v_div_fmas_f32 v38, v38, v39, v41
	v_div_fixup_f32 v0, v38, v0, 1.0
	ds_read_b128 v[38:41], v156
	ds_read_b128 v[42:45], v156 offset:64
	s_waitcnt lgkmcnt(1)
	v_mfma_f32_16x16x32_bf16 v[38:41], v[38:41], v[18:21], 0
	s_mov_b64 vcc, 0x100
	s_waitcnt lgkmcnt(0)
	v_mfma_f32_16x16x32_bf16 v[38:41], v[42:45], v[22:25], v[38:41]
	ds_read_b128 v[42:45], v156 offset:128
	s_waitcnt lgkmcnt(0)
	v_mfma_f32_16x16x32_bf16 v[38:41], v[42:45], v[26:29], v[38:41]
	ds_read_b128 v[42:45], v156 offset:192
	s_waitcnt lgkmcnt(0)
	v_mfma_f32_16x16x32_bf16 v[38:41], v[42:45], v[30:33], v[38:41]
	ds_read_b128 v[42:45], v156 offset:256
	s_waitcnt lgkmcnt(0)
	v_mfma_f32_16x16x32_bf16 v[38:41], v[42:45], v[34:37], v[38:41]
	s_nop 7
	v_mul_f32_e32 v38, v38, v0
	v_mul_f32_e32 v39, v39, v0
	v_cvt_pk_bf16_f32 v38, v38, v39
	v_mul_f32_e32 v39, v40, v0
	v_mul_f32_e32 v40, v41, v0
	v_cvt_pk_bf16_f32 v39, v39, v40
	global_store_dwordx2 v[90:91], v[38:39], off offset:-128
	ds_read_b128 v[38:41], v156 offset:8448
	ds_read_b128 v[42:45], v156 offset:8512
	s_waitcnt lgkmcnt(1)
	v_mfma_f32_16x16x32_bf16 v[38:41], v[38:41], v[18:21], 0
	s_waitcnt lgkmcnt(0)
	v_mfma_f32_16x16x32_bf16 v[38:41], v[42:45], v[22:25], v[38:41]
	ds_read_b128 v[42:45], v156 offset:8576
	s_waitcnt lgkmcnt(0)
	v_mfma_f32_16x16x32_bf16 v[38:41], v[42:45], v[26:29], v[38:41]
	ds_read_b128 v[42:45], v156 offset:8640
	s_waitcnt lgkmcnt(0)
	v_mfma_f32_16x16x32_bf16 v[38:41], v[42:45], v[30:33], v[38:41]
	ds_read_b128 v[42:45], v156 offset:8704
	s_waitcnt lgkmcnt(0)
	v_mfma_f32_16x16x32_bf16 v[38:41], v[42:45], v[34:37], v[38:41]
	s_nop 7
	v_mul_f32_e32 v38, v38, v0
	v_mul_f32_e32 v39, v39, v0
	v_cvt_pk_bf16_f32 v38, v38, v39
	v_mul_f32_e32 v39, v40, v0
	v_mul_f32_e32 v40, v41, v0
	v_cvt_pk_bf16_f32 v39, v39, v40
	global_store_dwordx2 v[90:91], v[38:39], off offset:-96
	ds_read_b128 v[38:41], v156 offset:16896
	ds_read_b128 v[42:45], v156 offset:16960
	s_waitcnt lgkmcnt(1)
	v_mfma_f32_16x16x32_bf16 v[38:41], v[38:41], v[18:21], 0
	s_waitcnt lgkmcnt(0)
	v_mfma_f32_16x16x32_bf16 v[38:41], v[42:45], v[22:25], v[38:41]
	ds_read_b128 v[42:45], v156 offset:17024
	s_waitcnt lgkmcnt(0)
	v_mfma_f32_16x16x32_bf16 v[38:41], v[42:45], v[26:29], v[38:41]
	ds_read_b128 v[42:45], v156 offset:17088
	s_waitcnt lgkmcnt(0)
	v_mfma_f32_16x16x32_bf16 v[38:41], v[42:45], v[30:33], v[38:41]
	ds_read_b128 v[42:45], v156 offset:17152
	s_waitcnt lgkmcnt(0)
	v_mfma_f32_16x16x32_bf16 v[38:41], v[42:45], v[34:37], v[38:41]
	s_nop 7
	v_mul_f32_e32 v38, v0, v38
	v_mul_f32_e32 v39, v0, v39
	v_cvt_pk_bf16_f32 v38, v38, v39
	v_mul_f32_e32 v39, v0, v40
	v_mul_f32_e32 v40, v0, v41
	v_cvt_pk_bf16_f32 v39, v39, v40
	global_store_dwordx2 v[90:91], v[38:39], off offset:-64
	ds_read_b128 v[38:41], v157
	ds_read_b128 v[42:45], v157 offset:64
	s_waitcnt lgkmcnt(1)
	v_mfma_f32_16x16x32_bf16 v[38:41], v[38:41], v[18:21], 0
	s_waitcnt lgkmcnt(0)
	v_mfma_f32_16x16x32_bf16 v[38:41], v[42:45], v[22:25], v[38:41]
	ds_read_b128 v[42:45], v157 offset:128
	s_waitcnt lgkmcnt(0)
	v_mfma_f32_16x16x32_bf16 v[38:41], v[42:45], v[26:29], v[38:41]
	ds_read_b128 v[42:45], v157 offset:192
	s_waitcnt lgkmcnt(0)
	v_mfma_f32_16x16x32_bf16 v[38:41], v[42:45], v[30:33], v[38:41]
	ds_read_b128 v[42:45], v157 offset:256
	s_waitcnt lgkmcnt(0)
	v_mfma_f32_16x16x32_bf16 v[38:41], v[42:45], v[34:37], v[38:41]
	s_nop 7
	v_mul_f32_e32 v38, v0, v38
	v_mul_f32_e32 v39, v0, v39
	v_cvt_pk_bf16_f32 v38, v38, v39
	v_mul_f32_e32 v39, v0, v40
	v_mul_f32_e32 v40, v0, v41
	v_cvt_pk_bf16_f32 v39, v39, v40
	global_store_dwordx2 v[90:91], v[38:39], off offset:-32
	ds_read_b128 v[38:41], v156 offset:33792
	ds_read_b128 v[42:45], v156 offset:33856
	s_waitcnt lgkmcnt(1)
; __device__ __forceinline__ unsigned cvt_pk_bf16(float lo, float hi) { unsigned r; asm volatile("v_cvt_pk_bf16_f32 %0, %1, %2" : "=v"(r) : "v"(lo), "v"(hi)); return r; }
; #define LAS __attribute__((address_space(3)))
; __device__ __forceinline__ void attn_unit(LAS unsigned char* lds, const bf16_t* PROJ, bf16_t* YCAT, const float* qg, const float* kg, const float* sinks, int unit, int tid, int wave, int lane) {
;     ...
; #pragma unroll
;     for (int db = 0; db < 8; ++db) {
;         f32x4 o = (f32x4){0.f, 0.f, 0.f, 0.f};
; #pragma unroll
;         for (int g = 0; g < 5; ++g) {
;             const bf16x8 vf = *(const LAS bf16x8*)(Vt + (16 * db + fr) * 264 + 32 * ((wp >> 1) + g) + 8 * fq);
;             o = __builtin_amdgcn_mfma_f32_16x16x32_bf16(vf, pf[g], o, 0, 0, 0);
;         }
;         u32x2 w; w.x = cvt_pk_bf16(o[0] * inv, o[1] * inv); w.y = cvt_pk_bf16(o[2] * inv, o[3] * inv);
;         *(u32x2*)(op + 16 * db) = w;
;     }
;     }
	v_mfma_f32_16x16x32_bf16 v[38:41], v[38:41], v[18:21], 0
	s_waitcnt lgkmcnt(0)
	v_mfma_f32_16x16x32_bf16 v[38:41], v[42:45], v[22:25], v[38:41]
	ds_read_b128 v[42:45], v156 offset:33920
	s_waitcnt lgkmcnt(0)
	v_mfma_f32_16x16x32_bf16 v[38:41], v[42:45], v[26:29], v[38:41]
	ds_read_b128 v[42:45], v156 offset:33984
	s_waitcnt lgkmcnt(0)
	v_mfma_f32_16x16x32_bf16 v[38:41], v[42:45], v[30:33], v[38:41]
	ds_read_b128 v[42:45], v156 offset:34048
	s_waitcnt lgkmcnt(0)
	v_mfma_f32_16x16x32_bf16 v[38:41], v[42:45], v[34:37], v[38:41]
	s_nop 7
	v_mul_f32_e32 v38, v0, v38
	v_mul_f32_e32 v39, v0, v39
	v_cvt_pk_bf16_f32 v38, v38, v39
	v_mul_f32_e32 v39, v0, v40
	v_mul_f32_e32 v40, v0, v41
	v_cvt_pk_bf16_f32 v39, v39, v40
	global_store_dwordx2 v[90:91], v[38:39], off
	ds_read_b128 v[38:41], v156 offset:42240
	ds_read_b128 v[42:45], v156 offset:42304
	s_waitcnt lgkmcnt(1)
	v_mfma_f32_16x16x32_bf16 v[38:41], v[38:41], v[18:21], 0
	s_waitcnt lgkmcnt(0)
	v_mfma_f32_16x16x32_bf16 v[38:41], v[42:45], v[22:25], v[38:41]
	ds_read_b128 v[42:45], v156 offset:42368
	s_waitcnt lgkmcnt(0)
	v_mfma_f32_16x16x32_bf16 v[38:41], v[42:45], v[26:29], v[38:41]
	ds_read_b128 v[42:45], v156 offset:42432
	s_waitcnt lgkmcnt(0)
	v_mfma_f32_16x16x32_bf16 v[38:41], v[42:45], v[30:33], v[38:41]
	ds_read_b128 v[42:45], v156 offset:42496
	s_waitcnt lgkmcnt(0)
	v_mfma_f32_16x16x32_bf16 v[38:41], v[42:45], v[34:37], v[38:41]
	s_nop 7
	v_mul_f32_e32 v38, v0, v38
	v_mul_f32_e32 v39, v0, v39
	v_cvt_pk_bf16_f32 v38, v38, v39
	v_mul_f32_e32 v39, v0, v40
	v_mul_f32_e32 v40, v0, v41
	v_cvt_pk_bf16_f32 v39, v39, v40
	global_store_dwordx2 v[90:91], v[38:39], off offset:32
	ds_read_b128 v[38:41], v156 offset:50688
	ds_read_b128 v[42:45], v156 offset:50752
	s_waitcnt lgkmcnt(1)
	v_mfma_f32_16x16x32_bf16 v[38:41], v[38:41], v[18:21], 0
	s_waitcnt lgkmcnt(0)
	v_mfma_f32_16x16x32_bf16 v[38:41], v[42:45], v[22:25], v[38:41]
	ds_read_b128 v[42:45], v156 offset:50816
	s_waitcnt lgkmcnt(0)
	v_mfma_f32_16x16x32_bf16 v[38:41], v[42:45], v[26:29], v[38:41]
	ds_read_b128 v[42:45], v156 offset:50880
	s_waitcnt lgkmcnt(0)
	v_mfma_f32_16x16x32_bf16 v[38:41], v[42:45], v[30:33], v[38:41]
	ds_read_b128 v[42:45], v156 offset:50944
	s_waitcnt lgkmcnt(0)
	v_mfma_f32_16x16x32_bf16 v[38:41], v[42:45], v[34:37], v[38:41]
	s_nop 7
	v_mul_f32_e32 v38, v0, v38
	v_mul_f32_e32 v39, v0, v39
	v_cvt_pk_bf16_f32 v38, v38, v39
	v_mul_f32_e32 v39, v0, v40
	v_mul_f32_e32 v40, v0, v41
	v_cvt_pk_bf16_f32 v39, v39, v40
	global_store_dwordx2 v[90:91], v[38:39], off offset:64
	ds_read_b128 v[38:41], v168
	s_waitcnt lgkmcnt(0)
	v_mfma_f32_16x16x32_bf16 v[18:21], v[38:41], v[18:21], 0
	ds_read_b128 v[38:41], v168 offset:64
	s_waitcnt lgkmcnt(0)
	v_mfma_f32_16x16x32_bf16 v[18:21], v[38:41], v[22:25], v[18:21]
	ds_read_b128 v[22:25], v168 offset:128
	s_waitcnt lgkmcnt(0)
	v_mfma_f32_16x16x32_bf16 v[18:21], v[22:25], v[26:29], v[18:21]
	ds_read_b128 v[22:25], v168 offset:192
	v_mov_b64_e32 v[28:29], v[8:9]
	v_mov_b64_e32 v[26:27], v[6:7]
	s_waitcnt lgkmcnt(0)
	v_mfma_f32_16x16x32_bf16 v[18:21], v[22:25], v[30:33], v[18:21]
	ds_read_b128 v[22:25], v168 offset:256
	v_mov_b64_e32 v[32:33], v[4:5]
	v_mov_b64_e32 v[30:31], v[2:3]
	s_waitcnt lgkmcnt(0)
	v_mfma_f32_16x16x32_bf16 v[18:21], v[22:25], v[34:37], v[18:21]
	v_mov_b64_e32 v[24:25], v[16:17]
	v_mov_b64_e32 v[22:23], v[14:15]
	s_nop 5
	v_mul_f32_e32 v18, v0, v18
	v_mul_f32_e32 v19, v0, v19
	v_cvt_pk_bf16_f32 v18, v18, v19
	v_mul_f32_e32 v19, v0, v20
	v_mul_f32_e32 v0, v0, v21
	v_cvt_pk_bf16_f32 v19, v19, v0
	global_store_dwordx2 v[90:91], v[18:19], off offset:96
	v_mov_b64_e32 v[20:21], v[12:13]
	v_lshl_add_u64 v[90:91], v[90:91], 0, vcc
	v_mov_b64_e32 v[18:19], v[10:11]
	s_cbranch_scc1 .LBB0_172
	v_readlane_b32 s2, v253, 54
	v_readlane_b32 s3, v253, 55
	s_add_i32 s83, s83, s2
	v_readlane_b32 s2, v253, 2
	s_add_i32 s82, s82, s2
	v_readlane_b32 s2, v253, 27
	v_readlane_b32 s24, v255, 45
	v_readlane_b32 s3, v253, 28
	v_readlane_b32 s25, v255, 46
	s_xor_b64 s[24:25], s[24:25], s[2:3]
	v_readlane_b32 s68, v254, 10
	s_mov_b32 s22, 0x800000
	s_cmpk_gt_i32 s83, 0xff
	v_readlane_b32 s23, v253, 59
	v_readlane_b32 s69, v254, 11
	s_barrier
	s_cbranch_scc0 .LBB0_157

; __device__ __forceinline__ unsigned cvt_pk_bf16(float lo, float hi) { unsigned r; asm volatile("v_cvt_pk_bf16_f32 %0, %1, %2" : "=v"(r) : "v"(lo), "v"(hi)); return r; }
; __device__ __forceinline__ float bf_lo(unsigned w) { return __uint_as_float(w << 16); }
; __device__ __forceinline__ float bf_hi(unsigned w) { return __uint_as_float(w & 0xffff0000u); }
; __device__ __forceinline__ void unpack8(u32x4 w, f32x4& a, f32x4& b) { a = (f32x4){bf_lo(w.x), bf_hi(w.x), bf_lo(w.y), bf_hi(w.y)}; b = (f32x4){bf_lo(w.z), bf_hi(w.z), bf_lo(w.w), bf_hi(w.w)}; }
; __device__ __forceinline__ void sg_unit(LAS unsigned char* lds, const bf16_t* PROJ, bf16_t* YCAT, const float* lng, const float* lnb, const float* sgw, const float* sgb, int unit, int tid, int wave, int lane) {
;     ...
;     {
;         const int c16 = tid & 15;
; #pragma unroll
;         for (int pass = 0; pass < 4; ++pass) {
;             const int r = (tid >> 4) + 32 * pass;
;             f32x4 v0, v1; pg8::unpack8(*(const u32x4*)(zv + (size_t)r * INW + 8 * c16), v0, v1);
;             float sm = (v0[0] + v0[1]) + (v0[2] + v0[3]) + (v1[0] + v1[1]) + (v1[2] + v1[3]);
;             sm += __shfl_xor(sm, 1); sm += __shfl_xor(sm, 2); sm += __shfl_xor(sm, 4); sm += __shfl_xor(sm, 8);
;             const float mean = sm * (1.f / 128.f);
;             v0 = v0 - mean; v1 = v1 - mean;
;             float q = (v0[0] * v0[0] + v0[1] * v0[1]) + (v0[2] * v0[2] + v0[3] * v0[3]) + (v1[0] * v1[0] + v1[1] * v1[1]) + (v1[2] * v1[2] + v1[3] * v1[3]);
;             q += __shfl_xor(q, 1); q += __shfl_xor(q, 2); q += __shfl_xor(q, 4); q += __shfl_xor(q, 8);
;             if (c16 == 0) { st[2 * r] = mean; st[2 * r + 1] = rsqrtf(q * (1.f / 128.f) + EPS); }
;         }
;     }
;     ...
;         const u32x2 zw = *(const u32x2*)(zu + 16 * cb);
;         u32x2 w; w.x = cvt_pk_bf16(bf_lo(zw.x) * (acc[0] + bs), bf_hi(zw.x) * (acc[1] + bs)); w.y = cvt_pk_bf16(bf_lo(zw.y) * (acc[2] + bs), bf_hi(zw.y) * (acc[3] + bs));
;         *(u32x2*)(op + 16 * cb) = w;
.LBB0_176:
	s_nop 0
	s_nop 5
	v_add_f32_e32 v2, v0, v2
	v_add_f32_e32 v3, v0, v3
	v_add_f32_e32 v4, v0, v4
	v_add_f32_e32 v0, v0, v5
	s_add_i32 s82, s82, s96
	s_cmpk_gt_i32 s82, 0x1ff
	s_waitcnt vmcnt(7)
	v_lshlrev_b32_e32 v5, 16, v190
	v_and_b32_e32 v6, 0xffff0000, v190
	v_lshlrev_b32_e32 v8, 16, v191
	v_and_b32_e32 v7, 0xffff0000, v191
	v_mul_f32_e32 v2, v2, v5
	v_mul_f32_e32 v3, v3, v6
	v_mul_f32_e32 v4, v4, v8
	v_mul_f32_e32 v0, v0, v7
	v_cvt_pk_bf16_f32 v2, v2, v3
	v_cvt_pk_bf16_f32 v3, v4, v0
	global_store_dwordx2 v[22:23], v[2:3], off offset:2272
	s_barrier
	s_cbranch_scc1 .LBB0_244
.LBB0_177:
	s_lshl_b32 s68, s82, 5
	s_and_b32 s83, s68, 0xffffff80
	s_mul_i32 s69, s83, 0x4800
	v_readlane_b32 s70, v254, 10
	s_mul_hi_i32 s68, s83, 0x4800
	v_readlane_b32 s71, v254, 11
	s_add_u32 s69, s70, s69
	s_addc_u32 s68, s71, s68
	s_lshl_b32 s70, s82, 7
	s_and_b32 s72, s70, 0x180
	s_lshl_b32 s78, s72, 1
	s_add_u32 s69, s69, s78
	s_addc_u32 s70, s68, 0
	s_add_u32 s68, s69, 0x1000
	s_addc_u32 s69, s70, 0
	v_mov_b32_e32 v45, v1
	v_lshl_add_u64 v[2:3], s[68:69], 0, v[44:45]
	v_lshl_add_u64 v[4:5], v[2:3], 0, v[34:35]
	global_load_dwordx4 v[4:7], v[4:5], off
	v_lshl_add_u64 v[220:221], v[2:3], 0, v[36:37]
	global_load_dwordx4 v[208:211], v[220:221], off
	v_lshl_add_u64 v[220:221], v[2:3], 0, v[38:39]
	global_load_dwordx4 v[212:215], v[220:221], off
	v_lshl_add_u64 v[220:221], v[2:3], 0, v[40:41]
	global_load_dwordx4 v[216:219], v[220:221], off
	s_waitcnt vmcnt(3)
	v_lshlrev_b32_e32 v9, 16, v5
	v_lshlrev_b32_e32 v8, 16, v4
	v_and_b32_e32 v5, 0xffff0000, v5
	v_and_b32_e32 v4, 0xffff0000, v4
	v_lshlrev_b32_e32 v11, 16, v7
	v_lshlrev_b32_e32 v10, 16, v6
	v_and_b32_e32 v7, 0xffff0000, v7
	v_and_b32_e32 v6, 0xffff0000, v6
	v_pk_add_f32 v[12:13], v[8:9], v[4:5]
	v_pk_add_f32 v[14:15], v[10:11], v[6:7]
	v_add_f32_e32 v0, v12, v13
	v_add_f32_e32 v0, v14, v0
	v_add_f32_e32 v0, v15, v0
	ds_bpermute_b32 v12, v48, v0
	s_waitcnt lgkmcnt(0)
	v_add_f32_e32 v0, v0, v12
	ds_bpermute_b32 v12, v49, v0
	s_waitcnt lgkmcnt(0)
	v_add_f32_e32 v0, v0, v12
	ds_bpermute_b32 v12, v50, v0
	s_waitcnt lgkmcnt(0)
	v_add_f32_e32 v0, v0, v12
	ds_bpermute_b32 v12, v51, v0
	s_waitcnt lgkmcnt(0)
	v_add_f32_e32 v0, v0, v12
	v_fmac_f32_e32 v5, 0xbc000000, v0
	v_fmac_f32_e32 v4, 0xbc000000, v0
	v_fmac_f32_e32 v9, 0xbc000000, v0
	v_fmac_f32_e32 v8, 0xbc000000, v0
	v_fmac_f32_e32 v6, 0xbc000000, v0
	v_mul_f32_e32 v4, v4, v4
	v_mul_f32_e32 v5, v5, v5
	v_fmac_f32_e32 v7, 0xbc000000, v0
	v_fmac_f32_e32 v10, 0xbc000000, v0
	v_mul_f32_e32 v6, v6, v6
	v_fmac_f32_e32 v4, v8, v8
	v_fmac_f32_e32 v5, v9, v9
	v_fmac_f32_e32 v11, 0xbc000000, v0
	v_mul_f32_e32 v7, v7, v7
	v_fmac_f32_e32 v6, v10, v10
	v_add_f32_e32 v4, v4, v5
	v_add_f32_e32 v4, v6, v4
	v_fmac_f32_e32 v7, v11, v11
	v_add_f32_e32 v4, v7, v4
	ds_bpermute_b32 v5, v48, v4
	s_waitcnt lgkmcnt(0)
	v_add_f32_e32 v4, v4, v5
	ds_bpermute_b32 v5, v49, v4
	s_waitcnt lgkmcnt(0)
	v_add_f32_e32 v4, v4, v5
	ds_bpermute_b32 v5, v50, v4
	s_waitcnt lgkmcnt(0)
	v_add_f32_e32 v4, v4, v5
	ds_bpermute_b32 v5, v51, v4
	s_and_saveexec_b64 s[70:71], s[0:1]
	s_cbranch_execz .LBB0_179
	s_waitcnt lgkmcnt(0)
	v_add_f32_e32 v4, v4, v5
	v_fmamk_f32 v4, v4, 0x3c000000, v197
	v_mul_f32_e32 v5, 0x4b800000, v4
	v_cmp_gt_f32_e32 vcc, s22, v4
	s_nop 1
	v_cndmask_b32_e32 v4, v4, v5, vcc
	v_rsq_f32_e32 v5, v4
	v_mul_f32_e32 v4, 0x3c000000, v0
	v_mul_f32_e32 v0, 0x45800000, v5
	v_cndmask_b32_e32 v5, v5, v0, vcc
	ds_write_b64 v52, v[4:5] offset:34816
.LBB0_179:
	s_or_b64 exec, exec, s[70:71]
	s_waitcnt lgkmcnt(0)
	v_lshl_add_u64 v[4:5], v[2:3], 0, v[36:37]
	s_nop 0
	s_waitcnt vmcnt(2)
	v_lshlrev_b32_e32 v9, 16, v209
	v_lshlrev_b32_e32 v8, 16, v208
	v_and_b32_e32 v5, 0xffff0000, v209
	v_and_b32_e32 v4, 0xffff0000, v208
	v_lshlrev_b32_e32 v11, 16, v211
	v_lshlrev_b32_e32 v10, 16, v210
	v_and_b32_e32 v7, 0xffff0000, v211
	v_and_b32_e32 v6, 0xffff0000, v210
	v_pk_add_f32 v[12:13], v[8:9], v[4:5]
	v_pk_add_f32 v[14:15], v[10:11], v[6:7]
	v_add_f32_e32 v0, v12, v13
	v_add_f32_e32 v0, v14, v0
	v_add_f32_e32 v0, v15, v0
	ds_bpermute_b32 v12, v48, v0
	s_waitcnt lgkmcnt(0)
	v_add_f32_e32 v0, v0, v12
	ds_bpermute_b32 v12, v49, v0
	s_waitcnt lgkmcnt(0)
	v_add_f32_e32 v0, v0, v12
	ds_bpermute_b32 v12, v50, v0
	s_waitcnt lgkmcnt(0)
	v_add_f32_e32 v0, v0, v12
	ds_bpermute_b32 v12, v51, v0
	s_waitcnt lgkmcnt(0)
	v_add_f32_e32 v0, v0, v12
	v_fmac_f32_e32 v5, 0xbc000000, v0
	v_fmac_f32_e32 v4, 0xbc000000, v0
	v_fmac_f32_e32 v9, 0xbc000000, v0
	v_fmac_f32_e32 v8, 0xbc000000, v0
	v_fmac_f32_e32 v6, 0xbc000000, v0
	v_mul_f32_e32 v4, v4, v4
	v_mul_f32_e32 v5, v5, v5
	v_fmac_f32_e32 v7, 0xbc000000, v0
	v_fmac_f32_e32 v10, 0xbc000000, v0
	v_mul_f32_e32 v6, v6, v6
	v_fmac_f32_e32 v4, v8, v8
	v_fmac_f32_e32 v5, v9, v9
	v_fmac_f32_e32 v11, 0xbc000000, v0
	v_mul_f32_e32 v7, v7, v7
	v_fmac_f32_e32 v6, v10, v10
	v_add_f32_e32 v4, v4, v5
	v_add_f32_e32 v4, v6, v4
	v_fmac_f32_e32 v7, v11, v11
	v_add_f32_e32 v4, v7, v4
	ds_bpermute_b32 v5, v48, v4
	s_waitcnt lgkmcnt(0)
	v_add_f32_e32 v4, v4, v5
	ds_bpermute_b32 v5, v49, v4
	s_waitcnt lgkmcnt(0)
	v_add_f32_e32 v4, v4, v5
	ds_bpermute_b32 v5, v50, v4
	s_waitcnt lgkmcnt(0)
	v_add_f32_e32 v4, v4, v5
	ds_bpermute_b32 v5, v51, v4
	s_and_saveexec_b64 s[70:71], s[0:1]
	s_cbranch_execz .LBB0_181
	s_waitcnt lgkmcnt(0)
	v_add_f32_e32 v4, v4, v5
	v_fmamk_f32 v4, v4, 0x3c000000, v197
	v_mul_f32_e32 v5, 0x4b800000, v4
	v_cmp_gt_f32_e32 vcc, s22, v4
	s_nop 1
	v_cndmask_b32_e32 v4, v4, v5, vcc
	v_rsq_f32_e32 v5, v4
	v_mul_f32_e32 v4, 0x3c000000, v0
	v_mul_f32_e32 v0, 0x45800000, v5
	v_cndmask_b32_e32 v5, v5, v0, vcc
	ds_write_b64 v53, v[4:5] offset:34816
; __device__ __forceinline__ void unpack8(u32x4 w, f32x4& a, f32x4& b) { a = (f32x4){bf_lo(w.x), bf_hi(w.x), bf_lo(w.y), bf_hi(w.y)}; b = (f32x4){bf_lo(w.z), bf_hi(w.z), bf_lo(w.w), bf_hi(w.w)}; }
; __device__ __forceinline__ void sg_unit(LAS unsigned char* lds, const bf16_t* PROJ, bf16_t* YCAT, const float* lng, const float* lnb, const float* sgw, const float* sgb, int unit, int tid, int wave, int lane) {
;     ...
;         for (int pass = 0; pass < 4; ++pass) {
;             const int r = (tid >> 4) + 32 * pass;
;             f32x4 v0, v1; pg8::unpack8(*(const u32x4*)(zv + (size_t)r * INW + 8 * c16), v0, v1);
;             float sm = (v0[0] + v0[1]) + (v0[2] + v0[3]) + (v1[0] + v1[1]) + (v1[2] + v1[3]);
;             sm += __shfl_xor(sm, 1); sm += __shfl_xor(sm, 2); sm += __shfl_xor(sm, 4); sm += __shfl_xor(sm, 8);
;             const float mean = sm * (1.f / 128.f);
;             v0 = v0 - mean; v1 = v1 - mean;
;             float q = (v0[0] * v0[0] + v0[1] * v0[1]) + (v0[2] * v0[2] + v0[3] * v0[3]) + (v1[0] * v1[0] + v1[1] * v1[1]) + (v1[2] * v1[2] + v1[3] * v1[3]);
;             q += __shfl_xor(q, 1); q += __shfl_xor(q, 2); q += __shfl_xor(q, 4); q += __shfl_xor(q, 8);
;             if (c16 == 0) { st[2 * r] = mean; st[2 * r + 1] = rsqrtf(q * (1.f / 128.f) + EPS); }
;         }
;     }
.LBB0_181:
	s_or_b64 exec, exec, s[70:71]
	s_waitcnt lgkmcnt(0)
	v_lshl_add_u64 v[4:5], v[2:3], 0, v[38:39]
	s_nop 0
	s_waitcnt vmcnt(1)
	v_lshlrev_b32_e32 v9, 16, v213
	v_lshlrev_b32_e32 v8, 16, v212
	v_and_b32_e32 v5, 0xffff0000, v213
	v_and_b32_e32 v4, 0xffff0000, v212
	v_lshlrev_b32_e32 v11, 16, v215
	v_lshlrev_b32_e32 v10, 16, v214
	v_and_b32_e32 v7, 0xffff0000, v215
	v_and_b32_e32 v6, 0xffff0000, v214
	v_pk_add_f32 v[12:13], v[8:9], v[4:5]
	v_pk_add_f32 v[14:15], v[10:11], v[6:7]
	v_add_f32_e32 v0, v12, v13
	v_add_f32_e32 v0, v14, v0
	v_add_f32_e32 v0, v15, v0
	ds_bpermute_b32 v12, v48, v0
	s_waitcnt lgkmcnt(0)
	v_add_f32_e32 v0, v0, v12
	ds_bpermute_b32 v12, v49, v0
	s_waitcnt lgkmcnt(0)
	v_add_f32_e32 v0, v0, v12
	ds_bpermute_b32 v12, v50, v0
	s_waitcnt lgkmcnt(0)
	v_add_f32_e32 v0, v0, v12
	ds_bpermute_b32 v12, v51, v0
	s_waitcnt lgkmcnt(0)
	v_add_f32_e32 v0, v0, v12
	v_fmac_f32_e32 v5, 0xbc000000, v0
	v_fmac_f32_e32 v4, 0xbc000000, v0
	v_fmac_f32_e32 v9, 0xbc000000, v0
	v_fmac_f32_e32 v8, 0xbc000000, v0
	v_fmac_f32_e32 v6, 0xbc000000, v0
	v_mul_f32_e32 v4, v4, v4
	v_mul_f32_e32 v5, v5, v5
	v_fmac_f32_e32 v7, 0xbc000000, v0
	v_fmac_f32_e32 v10, 0xbc000000, v0
	v_mul_f32_e32 v6, v6, v6
	v_fmac_f32_e32 v4, v8, v8
	v_fmac_f32_e32 v5, v9, v9
	v_fmac_f32_e32 v11, 0xbc000000, v0
	v_mul_f32_e32 v7, v7, v7
	v_fmac_f32_e32 v6, v10, v10
	v_add_f32_e32 v4, v4, v5
	v_add_f32_e32 v4, v6, v4
	v_fmac_f32_e32 v7, v11, v11
	v_add_f32_e32 v4, v7, v4
	ds_bpermute_b32 v5, v48, v4
	s_waitcnt lgkmcnt(0)
	v_add_f32_e32 v4, v4, v5
	ds_bpermute_b32 v5, v49, v4
	s_waitcnt lgkmcnt(0)
	v_add_f32_e32 v4, v4, v5
	ds_bpermute_b32 v5, v50, v4
	s_waitcnt lgkmcnt(0)
	v_add_f32_e32 v4, v4, v5
	ds_bpermute_b32 v5, v51, v4
	s_and_saveexec_b64 s[70:71], s[0:1]
	s_cbranch_execz .LBB0_183
	s_waitcnt lgkmcnt(0)
	v_add_f32_e32 v4, v4, v5
	v_fmamk_f32 v4, v4, 0x3c000000, v197
	v_mul_f32_e32 v5, 0x4b800000, v4
	v_cmp_gt_f32_e32 vcc, s22, v4
	s_nop 1
	v_cndmask_b32_e32 v4, v4, v5, vcc
	v_rsq_f32_e32 v5, v4
	v_mul_f32_e32 v4, 0x3c000000, v0
	v_mul_f32_e32 v0, 0x45800000, v5
	v_cndmask_b32_e32 v5, v5, v0, vcc
	ds_write_b64 v54, v[4:5] offset:34816
.LBB0_183:
	s_or_b64 exec, exec, s[70:71]
	v_lshl_add_u64 v[2:3], v[2:3], 0, v[40:41]
	s_waitcnt lgkmcnt(0)
	s_nop 0
	s_waitcnt vmcnt(0)
	v_lshlrev_b32_e32 v7, 16, v217
	v_lshlrev_b32_e32 v6, 16, v216
	v_and_b32_e32 v3, 0xffff0000, v217
	v_and_b32_e32 v2, 0xffff0000, v216
	v_lshlrev_b32_e32 v9, 16, v219
	v_lshlrev_b32_e32 v8, 16, v218
	v_and_b32_e32 v5, 0xffff0000, v219
	v_and_b32_e32 v4, 0xffff0000, v218
	v_pk_add_f32 v[10:11], v[6:7], v[2:3]
	v_pk_add_f32 v[12:13], v[8:9], v[4:5]
	v_add_f32_e32 v0, v10, v11
	v_add_f32_e32 v0, v12, v0
	v_add_f32_e32 v0, v13, v0
	ds_bpermute_b32 v10, v48, v0
	s_waitcnt lgkmcnt(0)
	v_add_f32_e32 v0, v0, v10
	ds_bpermute_b32 v10, v49, v0
	s_waitcnt lgkmcnt(0)
	v_add_f32_e32 v0, v0, v10
	ds_bpermute_b32 v10, v50, v0
	s_waitcnt lgkmcnt(0)
	v_add_f32_e32 v0, v0, v10
	ds_bpermute_b32 v10, v51, v0
	s_waitcnt lgkmcnt(0)
	v_add_f32_e32 v0, v0, v10
	v_fmac_f32_e32 v3, 0xbc000000, v0
	v_fmac_f32_e32 v2, 0xbc000000, v0
	v_fmac_f32_e32 v7, 0xbc000000, v0
	v_fmac_f32_e32 v6, 0xbc000000, v0
	v_fmac_f32_e32 v4, 0xbc000000, v0
	v_mul_f32_e32 v2, v2, v2
	v_mul_f32_e32 v3, v3, v3
	v_fmac_f32_e32 v5, 0xbc000000, v0
	v_fmac_f32_e32 v8, 0xbc000000, v0
	v_mul_f32_e32 v4, v4, v4
	v_fmac_f32_e32 v2, v6, v6
	v_fmac_f32_e32 v3, v7, v7
	v_fmac_f32_e32 v9, 0xbc000000, v0
	v_mul_f32_e32 v5, v5, v5
	v_fmac_f32_e32 v4, v8, v8
	v_add_f32_e32 v2, v2, v3
	v_add_f32_e32 v2, v4, v2
	v_fmac_f32_e32 v5, v9, v9
	v_add_f32_e32 v2, v5, v2
	ds_bpermute_b32 v3, v48, v2
	s_waitcnt lgkmcnt(0)
	v_add_f32_e32 v2, v2, v3
	ds_bpermute_b32 v3, v49, v2
	s_waitcnt lgkmcnt(0)
	v_add_f32_e32 v2, v2, v3
	ds_bpermute_b32 v3, v50, v2
	s_waitcnt lgkmcnt(0)
	v_add_f32_e32 v2, v2, v3
	ds_bpermute_b32 v3, v51, v2
	s_and_saveexec_b64 s[70:71], s[0:1]
	s_cbranch_execz .LBB0_185
	s_waitcnt lgkmcnt(0)
	v_add_f32_e32 v2, v2, v3
	v_fmamk_f32 v2, v2, 0x3c000000, v197
	v_mul_f32_e32 v3, 0x4b800000, v2
	v_cmp_gt_f32_e32 vcc, s22, v2
	s_nop 1
	v_cndmask_b32_e32 v2, v2, v3, vcc
	v_rsq_f32_e32 v3, v2
	v_mul_f32_e32 v2, 0x3c000000, v0
	v_mul_f32_e32 v0, 0x45800000, v3
	v_cndmask_b32_e32 v3, v3, v0, vcc
	ds_write_b64 v55, v[2:3] offset:34816

; __device__ __forceinline__ unsigned cvt_pk_bf16(float lo, float hi) { unsigned r; asm volatile("v_cvt_pk_bf16_f32 %0, %1, %2" : "=v"(r) : "v"(lo), "v"(hi)); return r; }
; __device__ __forceinline__ float bf_lo(unsigned w) { return __uint_as_float(w << 16); }
; __device__ __forceinline__ float bf_hi(unsigned w) { return __uint_as_float(w & 0xffff0000u); }
; #define LAS __attribute__((address_space(3)))
; __device__ __forceinline__ void sg_unit(LAS unsigned char* lds, const bf16_t* PROJ, bf16_t* YCAT, const float* lng, const float* lnb, const float* sgw, const float* sgb, int unit, int tid, int wave, int lane) {
;     ...
;     const bf16_t* zu = PROJ + (size_t)(t0 + t) * INW + 1536 + g * 128 + 4 * fq;
;     bf16_t* op = YCAT + (size_t)(t0 + t) * D + 1024 + g * 128 + 4 * fq;
; #pragma unroll
;     for (int cb = 0; cb < 8; ++cb) {
;         f32x4 acc = (f32x4){0.f, 0.f, 0.f, 0.f};
; #pragma unroll
;         for (int ks = 0; ks < 4; ++ks) if (ks < nks) {
;             const bf16x8 zf = *(const LAS bf16x8*)(Zt + (16 * cb + fr) * 136 + 32 * ks + 8 * fq);
;             acc = __builtin_amdgcn_mfma_f32_16x16x32_bf16(zf, wf[ks], acc, 0, 0, 0);
;         }
;         const u32x2 zw = *(const u32x2*)(zu + 16 * cb);
;         u32x2 w; w.x = cvt_pk_bf16(bf_lo(zw.x) * (acc[0] + bs), bf_hi(zw.x) * (acc[1] + bs)); w.y = cvt_pk_bf16(bf_lo(zw.y) * (acc[2] + bs), bf_hi(zw.y) * (acc[3] + bs));
;         *(u32x2*)(op + 16 * cb) = w;
.LBB0_200:
	v_readlane_b32 s86, v254, 10
	v_readlane_b32 s87, v254, 11
	v_add_u32_e32 v22, s83, v73
	v_mov_b32_e32 v47, v1
	v_mov_b64_e32 v[24:25], s[86:87]
	v_mad_i64_i32 v[24:25], s[86:87], v22, s81, v[24:25]
	v_lshl_add_u64 v[24:25], v[24:25], 0, s[78:79]
	v_lshl_add_u64 v[24:25], v[24:25], 0, v[46:47]
	global_load_dwordx2 v[176:177], v[24:25], off offset:3072
	global_load_dwordx2 v[178:179], v[24:25], off offset:3104
	global_load_dwordx2 v[180:181], v[24:25], off offset:3136
	global_load_dwordx2 v[182:183], v[24:25], off offset:3168
	global_load_dwordx2 v[184:185], v[24:25], off offset:3200
	global_load_dwordx2 v[186:187], v[24:25], off offset:3232
	global_load_dwordx2 v[188:189], v[24:25], off offset:3264
	global_load_dwordx2 v[190:191], v[24:25], off offset:3296
	v_ashrrev_i32_e32 v23, 31, v22
	v_readlane_b32 s86, v253, 62
	s_waitcnt vmcnt(8)
	v_add_f32_e32 v18, v0, v18
	v_add_f32_e32 v19, v0, v19
	v_lshlrev_b64 v[22:23], 12, v[22:23]
	v_readlane_b32 s87, v253, 63
	v_add_f32_e32 v20, v0, v20
	v_add_f32_e32 v21, v0, v21
	v_lshl_add_u64 v[22:23], s[86:87], 0, v[22:23]
	v_lshl_add_u64 v[22:23], v[22:23], 0, s[78:79]
	v_lshl_add_u64 v[22:23], v[22:23], 0, v[46:47]
	s_and_b64 vcc, exec, s[72:73]
	s_waitcnt vmcnt(7)
	v_lshlrev_b32_e32 v28, 16, v176
	v_and_b32_e32 v26, 0xffff0000, v176
	v_mul_f32_e32 v18, v18, v28
	v_mul_f32_e32 v19, v19, v26
	v_cvt_pk_bf16_f32 v18, v18, v19
	v_lshlrev_b32_e32 v19, 16, v177
	v_mul_f32_e32 v19, v20, v19
	v_and_b32_e32 v20, 0xffff0000, v177
	v_mul_f32_e32 v20, v21, v20
	v_cvt_pk_bf16_f32 v19, v19, v20
	global_store_dwordx2 v[22:23], v[18:19], off offset:2048
	ds_read_b128 v[18:21], v56 offset:4352
	s_waitcnt lgkmcnt(0)
	v_mfma_f32_16x16x32_bf16 v[18:21], v[18:21], v[2:5], 0
	s_cbranch_vccnz .LBB0_229
	ds_read_b128 v[26:29], v56 offset:4416
	s_waitcnt lgkmcnt(0)
	v_mfma_f32_16x16x32_bf16 v[18:21], v[26:29], v[6:9], v[18:21]
	s_and_b64 vcc, exec, s[68:69]
	s_cbranch_vccz .LBB0_230

; __device__ __forceinline__ unsigned cvt_pk_bf16(float lo, float hi) { unsigned r; asm volatile("v_cvt_pk_bf16_f32 %0, %1, %2" : "=v"(r) : "v"(lo), "v"(hi)); return r; }
; __device__ __forceinline__ float bf_lo(unsigned w) { return __uint_as_float(w << 16); }
; __device__ __forceinline__ float bf_hi(unsigned w) { return __uint_as_float(w & 0xffff0000u); }
; #define LAS __attribute__((address_space(3)))
; __device__ __forceinline__ void sg_unit(LAS unsigned char* lds, const bf16_t* PROJ, bf16_t* YCAT, const float* lng, const float* lnb, const float* sgw, const float* sgb, int unit, int tid, int wave, int lane) {
;     ...
;     for (int cb = 0; cb < 8; ++cb) {
;         f32x4 acc = (f32x4){0.f, 0.f, 0.f, 0.f};
; #pragma unroll
;         for (int ks = 0; ks < 4; ++ks) if (ks < nks) {
;             const bf16x8 zf = *(const LAS bf16x8*)(Zt + (16 * cb + fr) * 136 + 32 * ks + 8 * fq);
;             acc = __builtin_amdgcn_mfma_f32_16x16x32_bf16(zf, wf[ks], acc, 0, 0, 0);
;         }
;         const u32x2 zw = *(const u32x2*)(zu + 16 * cb);
;         u32x2 w; w.x = cvt_pk_bf16(bf_lo(zw.x) * (acc[0] + bs), bf_hi(zw.x) * (acc[1] + bs)); w.y = cvt_pk_bf16(bf_lo(zw.y) * (acc[2] + bs), bf_hi(zw.y) * (acc[3] + bs));
;         *(u32x2*)(op + 16 * cb) = w;
.LBB0_204:
	s_nop 0
	s_nop 6
	v_add_f32_e32 v18, v0, v18
	v_add_f32_e32 v19, v0, v19
	v_add_f32_e32 v20, v0, v20
	v_add_f32_e32 v21, v0, v21
	s_and_b64 vcc, exec, s[72:73]
	s_waitcnt vmcnt(7)
	v_lshlrev_b32_e32 v28, 16, v178
	v_and_b32_e32 v26, 0xffff0000, v178
	v_mul_f32_e32 v18, v18, v28
	v_mul_f32_e32 v19, v19, v26
	v_cvt_pk_bf16_f32 v18, v18, v19
	v_lshlrev_b32_e32 v19, 16, v179
	v_mul_f32_e32 v19, v20, v19
	v_and_b32_e32 v20, 0xffff0000, v179
	v_mul_f32_e32 v20, v21, v20
	v_cvt_pk_bf16_f32 v19, v19, v20
	global_store_dwordx2 v[22:23], v[18:19], off offset:2080
	ds_read_b128 v[18:21], v56 offset:8704
	s_waitcnt lgkmcnt(0)
	v_mfma_f32_16x16x32_bf16 v[18:21], v[18:21], v[2:5], 0
	s_cbranch_vccnz .LBB0_231
	ds_read_b128 v[26:29], v56 offset:8768
	s_waitcnt lgkmcnt(0)
	v_mfma_f32_16x16x32_bf16 v[18:21], v[26:29], v[6:9], v[18:21]
	s_and_b64 vcc, exec, s[68:69]
	s_cbranch_vccz .LBB0_232

; __device__ __forceinline__ unsigned cvt_pk_bf16(float lo, float hi) { unsigned r; asm volatile("v_cvt_pk_bf16_f32 %0, %1, %2" : "=v"(r) : "v"(lo), "v"(hi)); return r; }
; __device__ __forceinline__ float bf_lo(unsigned w) { return __uint_as_float(w << 16); }
; __device__ __forceinline__ float bf_hi(unsigned w) { return __uint_as_float(w & 0xffff0000u); }
; #define LAS __attribute__((address_space(3)))
; __device__ __forceinline__ void sg_unit(LAS unsigned char* lds, const bf16_t* PROJ, bf16_t* YCAT, const float* lng, const float* lnb, const float* sgw, const float* sgb, int unit, int tid, int wave, int lane) {
;     ...
;     for (int cb = 0; cb < 8; ++cb) {
;         f32x4 acc = (f32x4){0.f, 0.f, 0.f, 0.f};
; #pragma unroll
;         for (int ks = 0; ks < 4; ++ks) if (ks < nks) {
;             const bf16x8 zf = *(const LAS bf16x8*)(Zt + (16 * cb + fr) * 136 + 32 * ks + 8 * fq);
;             acc = __builtin_amdgcn_mfma_f32_16x16x32_bf16(zf, wf[ks], acc, 0, 0, 0);
;         }
;         const u32x2 zw = *(const u32x2*)(zu + 16 * cb);
;         u32x2 w; w.x = cvt_pk_bf16(bf_lo(zw.x) * (acc[0] + bs), bf_hi(zw.x) * (acc[1] + bs)); w.y = cvt_pk_bf16(bf_lo(zw.y) * (acc[2] + bs), bf_hi(zw.y) * (acc[3] + bs));
;         *(u32x2*)(op + 16 * cb) = w;
.LBB0_208:
	s_nop 0
	s_nop 6
	v_add_f32_e32 v18, v0, v18
	v_add_f32_e32 v19, v0, v19
	v_add_f32_e32 v20, v0, v20
	v_add_f32_e32 v21, v0, v21
	s_and_b64 vcc, exec, s[72:73]
	s_waitcnt vmcnt(7)
	v_lshlrev_b32_e32 v28, 16, v180
	v_and_b32_e32 v26, 0xffff0000, v180
	v_mul_f32_e32 v18, v18, v28
	v_mul_f32_e32 v19, v19, v26
	v_cvt_pk_bf16_f32 v18, v18, v19
	v_lshlrev_b32_e32 v19, 16, v181
	v_mul_f32_e32 v19, v20, v19
	v_and_b32_e32 v20, 0xffff0000, v181
	v_mul_f32_e32 v20, v21, v20
	v_cvt_pk_bf16_f32 v19, v19, v20
	global_store_dwordx2 v[22:23], v[18:19], off offset:2112
	ds_read_b128 v[18:21], v57
	s_waitcnt lgkmcnt(0)
	v_mfma_f32_16x16x32_bf16 v[18:21], v[18:21], v[2:5], 0
	s_cbranch_vccnz .LBB0_233
	ds_read_b128 v[26:29], v57 offset:64
	s_waitcnt lgkmcnt(0)
	v_mfma_f32_16x16x32_bf16 v[18:21], v[26:29], v[6:9], v[18:21]
	s_and_b64 vcc, exec, s[68:69]
	s_cbranch_vccz .LBB0_234

; __device__ __forceinline__ unsigned cvt_pk_bf16(float lo, float hi) { unsigned r; asm volatile("v_cvt_pk_bf16_f32 %0, %1, %2" : "=v"(r) : "v"(lo), "v"(hi)); return r; }
; __device__ __forceinline__ float bf_lo(unsigned w) { return __uint_as_float(w << 16); }
; __device__ __forceinline__ float bf_hi(unsigned w) { return __uint_as_float(w & 0xffff0000u); }
; #define LAS __attribute__((address_space(3)))
; __device__ __forceinline__ void sg_unit(LAS unsigned char* lds, const bf16_t* PROJ, bf16_t* YCAT, const float* lng, const float* lnb, const float* sgw, const float* sgb, int unit, int tid, int wave, int lane) {
;     ...
;     for (int cb = 0; cb < 8; ++cb) {
;         f32x4 acc = (f32x4){0.f, 0.f, 0.f, 0.f};
; #pragma unroll
;         for (int ks = 0; ks < 4; ++ks) if (ks < nks) {
;             const bf16x8 zf = *(const LAS bf16x8*)(Zt + (16 * cb + fr) * 136 + 32 * ks + 8 * fq);
;             acc = __builtin_amdgcn_mfma_f32_16x16x32_bf16(zf, wf[ks], acc, 0, 0, 0);
;         }
;         const u32x2 zw = *(const u32x2*)(zu + 16 * cb);
;         u32x2 w; w.x = cvt_pk_bf16(bf_lo(zw.x) * (acc[0] + bs), bf_hi(zw.x) * (acc[1] + bs)); w.y = cvt_pk_bf16(bf_lo(zw.y) * (acc[2] + bs), bf_hi(zw.y) * (acc[3] + bs));
;         *(u32x2*)(op + 16 * cb) = w;
.LBB0_212:
	s_nop 0
	s_nop 6
	v_add_f32_e32 v18, v0, v18
	v_add_f32_e32 v19, v0, v19
	v_add_f32_e32 v20, v0, v20
	v_add_f32_e32 v21, v0, v21
	s_and_b64 vcc, exec, s[72:73]
	s_waitcnt vmcnt(7)
	v_lshlrev_b32_e32 v28, 16, v182
	v_and_b32_e32 v26, 0xffff0000, v182
	v_mul_f32_e32 v18, v18, v28
	v_mul_f32_e32 v19, v19, v26
	v_cvt_pk_bf16_f32 v18, v18, v19
	v_lshlrev_b32_e32 v19, 16, v183
	v_mul_f32_e32 v19, v20, v19
	v_and_b32_e32 v20, 0xffff0000, v183
	v_mul_f32_e32 v20, v21, v20
	v_cvt_pk_bf16_f32 v19, v19, v20
	global_store_dwordx2 v[22:23], v[18:19], off offset:2144
	ds_read_b128 v[18:21], v56 offset:17408
	s_waitcnt lgkmcnt(0)
	v_mfma_f32_16x16x32_bf16 v[18:21], v[18:21], v[2:5], 0
	s_cbranch_vccnz .LBB0_235
	ds_read_b128 v[26:29], v56 offset:17472
	s_waitcnt lgkmcnt(0)
	v_mfma_f32_16x16x32_bf16 v[18:21], v[26:29], v[6:9], v[18:21]
	s_and_b64 vcc, exec, s[68:69]
	s_cbranch_vccz .LBB0_236

; __device__ __forceinline__ unsigned cvt_pk_bf16(float lo, float hi) { unsigned r; asm volatile("v_cvt_pk_bf16_f32 %0, %1, %2" : "=v"(r) : "v"(lo), "v"(hi)); return r; }
; __device__ __forceinline__ float bf_lo(unsigned w) { return __uint_as_float(w << 16); }
; __device__ __forceinline__ float bf_hi(unsigned w) { return __uint_as_float(w & 0xffff0000u); }
; #define LAS __attribute__((address_space(3)))
; __device__ __forceinline__ void sg_unit(LAS unsigned char* lds, const bf16_t* PROJ, bf16_t* YCAT, const float* lng, const float* lnb, const float* sgw, const float* sgb, int unit, int tid, int wave, int lane) {
;     ...
;     for (int cb = 0; cb < 8; ++cb) {
;         f32x4 acc = (f32x4){0.f, 0.f, 0.f, 0.f};
; #pragma unroll
;         for (int ks = 0; ks < 4; ++ks) if (ks < nks) {
;             const bf16x8 zf = *(const LAS bf16x8*)(Zt + (16 * cb + fr) * 136 + 32 * ks + 8 * fq);
;             acc = __builtin_amdgcn_mfma_f32_16x16x32_bf16(zf, wf[ks], acc, 0, 0, 0);
;         }
;         const u32x2 zw = *(const u32x2*)(zu + 16 * cb);
;         u32x2 w; w.x = cvt_pk_bf16(bf_lo(zw.x) * (acc[0] + bs), bf_hi(zw.x) * (acc[1] + bs)); w.y = cvt_pk_bf16(bf_lo(zw.y) * (acc[2] + bs), bf_hi(zw.y) * (acc[3] + bs));
;         *(u32x2*)(op + 16 * cb) = w;
.LBB0_216:
	s_nop 0
	s_nop 6
	v_add_f32_e32 v18, v0, v18
	v_add_f32_e32 v19, v0, v19
	v_add_f32_e32 v20, v0, v20
	v_add_f32_e32 v21, v0, v21
	s_and_b64 vcc, exec, s[72:73]
	s_waitcnt vmcnt(7)
	v_lshlrev_b32_e32 v28, 16, v184
	v_and_b32_e32 v26, 0xffff0000, v184
	v_mul_f32_e32 v18, v18, v28
	v_mul_f32_e32 v19, v19, v26
	v_cvt_pk_bf16_f32 v18, v18, v19
	v_lshlrev_b32_e32 v19, 16, v185
	v_mul_f32_e32 v19, v20, v19
	v_and_b32_e32 v20, 0xffff0000, v185
	v_mul_f32_e32 v20, v21, v20
	v_cvt_pk_bf16_f32 v19, v19, v20
	global_store_dwordx2 v[22:23], v[18:19], off offset:2176
	ds_read_b128 v[18:21], v56 offset:21760
	s_waitcnt lgkmcnt(0)
	v_mfma_f32_16x16x32_bf16 v[18:21], v[18:21], v[2:5], 0
	s_cbranch_vccnz .LBB0_237
	ds_read_b128 v[26:29], v56 offset:21824
	s_waitcnt lgkmcnt(0)
	v_mfma_f32_16x16x32_bf16 v[18:21], v[26:29], v[6:9], v[18:21]
	s_and_b64 vcc, exec, s[68:69]
	s_cbranch_vccz .LBB0_238

; __device__ __forceinline__ unsigned cvt_pk_bf16(float lo, float hi) { unsigned r; asm volatile("v_cvt_pk_bf16_f32 %0, %1, %2" : "=v"(r) : "v"(lo), "v"(hi)); return r; }
; __device__ __forceinline__ float bf_lo(unsigned w) { return __uint_as_float(w << 16); }
; __device__ __forceinline__ float bf_hi(unsigned w) { return __uint_as_float(w & 0xffff0000u); }
; #define LAS __attribute__((address_space(3)))
; __device__ __forceinline__ void sg_unit(LAS unsigned char* lds, const bf16_t* PROJ, bf16_t* YCAT, const float* lng, const float* lnb, const float* sgw, const float* sgb, int unit, int tid, int wave, int lane) {
;     ...
;     for (int cb = 0; cb < 8; ++cb) {
;         f32x4 acc = (f32x4){0.f, 0.f, 0.f, 0.f};
; #pragma unroll
;         for (int ks = 0; ks < 4; ++ks) if (ks < nks) {
;             const bf16x8 zf = *(const LAS bf16x8*)(Zt + (16 * cb + fr) * 136 + 32 * ks + 8 * fq);
;             acc = __builtin_amdgcn_mfma_f32_16x16x32_bf16(zf, wf[ks], acc, 0, 0, 0);
;         }
;         const u32x2 zw = *(const u32x2*)(zu + 16 * cb);
;         u32x2 w; w.x = cvt_pk_bf16(bf_lo(zw.x) * (acc[0] + bs), bf_hi(zw.x) * (acc[1] + bs)); w.y = cvt_pk_bf16(bf_lo(zw.y) * (acc[2] + bs), bf_hi(zw.y) * (acc[3] + bs));
;         *(u32x2*)(op + 16 * cb) = w;
.LBB0_220:
	s_nop 0
	s_nop 6
	v_add_f32_e32 v18, v0, v18
	v_add_f32_e32 v19, v0, v19
	v_add_f32_e32 v20, v0, v20
	v_add_f32_e32 v21, v0, v21
	s_and_b64 vcc, exec, s[72:73]
	s_waitcnt vmcnt(7)
	v_lshlrev_b32_e32 v28, 16, v186
	v_and_b32_e32 v26, 0xffff0000, v186
	v_mul_f32_e32 v18, v18, v28
	v_mul_f32_e32 v19, v19, v26
	v_cvt_pk_bf16_f32 v18, v18, v19
	v_lshlrev_b32_e32 v19, 16, v187
	v_mul_f32_e32 v19, v20, v19
	v_and_b32_e32 v20, 0xffff0000, v187
	v_mul_f32_e32 v20, v21, v20
	v_cvt_pk_bf16_f32 v19, v19, v20
	global_store_dwordx2 v[22:23], v[18:19], off offset:2208
	ds_read_b128 v[18:21], v56 offset:26112
	s_waitcnt lgkmcnt(0)
	v_mfma_f32_16x16x32_bf16 v[18:21], v[18:21], v[2:5], 0
	s_cbranch_vccnz .LBB0_239
	ds_read_b128 v[26:29], v56 offset:26176
	s_waitcnt lgkmcnt(0)
	v_mfma_f32_16x16x32_bf16 v[18:21], v[26:29], v[6:9], v[18:21]
	s_and_b64 vcc, exec, s[68:69]
	s_cbranch_vccz .LBB0_240

; __device__ __forceinline__ unsigned cvt_pk_bf16(float lo, float hi) { unsigned r; asm volatile("v_cvt_pk_bf16_f32 %0, %1, %2" : "=v"(r) : "v"(lo), "v"(hi)); return r; }
; __device__ __forceinline__ float bf_lo(unsigned w) { return __uint_as_float(w << 16); }
; __device__ __forceinline__ float bf_hi(unsigned w) { return __uint_as_float(w & 0xffff0000u); }
; #define LAS __attribute__((address_space(3)))
; __device__ __forceinline__ void sg_unit(LAS unsigned char* lds, const bf16_t* PROJ, bf16_t* YCAT, const float* lng, const float* lnb, const float* sgw, const float* sgb, int unit, int tid, int wave, int lane) {
;     ...
;     for (int cb = 0; cb < 8; ++cb) {
;         f32x4 acc = (f32x4){0.f, 0.f, 0.f, 0.f};
; #pragma unroll
;         for (int ks = 0; ks < 4; ++ks) if (ks < nks) {
;             const bf16x8 zf = *(const LAS bf16x8*)(Zt + (16 * cb + fr) * 136 + 32 * ks + 8 * fq);
;             acc = __builtin_amdgcn_mfma_f32_16x16x32_bf16(zf, wf[ks], acc, 0, 0, 0);
;         }
;         const u32x2 zw = *(const u32x2*)(zu + 16 * cb);
;         u32x2 w; w.x = cvt_pk_bf16(bf_lo(zw.x) * (acc[0] + bs), bf_hi(zw.x) * (acc[1] + bs)); w.y = cvt_pk_bf16(bf_lo(zw.y) * (acc[2] + bs), bf_hi(zw.y) * (acc[3] + bs));
;         *(u32x2*)(op + 16 * cb) = w;
.LBB0_224:
	s_nop 0
	s_nop 6
	v_add_f32_e32 v18, v0, v18
	v_add_f32_e32 v19, v0, v19
	v_add_f32_e32 v20, v0, v20
	v_add_f32_e32 v21, v0, v21
	s_and_b64 vcc, exec, s[72:73]
	s_waitcnt vmcnt(7)
	v_lshlrev_b32_e32 v28, 16, v188
	v_and_b32_e32 v26, 0xffff0000, v188
	v_mul_f32_e32 v18, v18, v28
	v_mul_f32_e32 v19, v19, v26
	v_cvt_pk_bf16_f32 v18, v18, v19
	v_lshlrev_b32_e32 v19, 16, v189
	v_mul_f32_e32 v19, v20, v19
	v_and_b32_e32 v20, 0xffff0000, v189
	v_mul_f32_e32 v20, v21, v20
	v_cvt_pk_bf16_f32 v19, v19, v20
	global_store_dwordx2 v[22:23], v[18:19], off offset:2240
	ds_read_b128 v[18:21], v58
	s_waitcnt lgkmcnt(0)
	v_mfma_f32_16x16x32_bf16 v[2:5], v[18:21], v[2:5], 0
	s_cbranch_vccnz .LBB0_241
	ds_read_b128 v[18:21], v58 offset:64
	s_waitcnt lgkmcnt(0)
	v_mfma_f32_16x16x32_bf16 v[2:5], v[18:21], v[6:9], v[2:5]
	s_and_b64 vcc, exec, s[68:69]
	s_cbranch_vccz .LBB0_242
